# adds hoisted gain loads in retention/GLA output tails (8 loads up front, stale vmcnt(0) waits removed)
# speedup vs baseline: 1.0243x; 1.0243x over previous
; #define LAS __attribute__((address_space(3)))
; #define MFMA16(a, b, c) __builtin_amdgcn_mfma_f32_16x16x32_bf16((a), (b), (c), 0, 0, 0)
; DI void wave_ret_out(CP p, int l, int u, int ih, int lane, LAS unsigned char* vl) {
;     ...
; #pragma unroll
;     for (int hh = 0; hh < 2; ++hh) { u32x4 vv[8];
; #pragma unroll
;         for (int i = 0; i < 8; ++i) vv[i] = *(const u32x4*)(rowb + (size_t)(32 * hh + 4 * i + g) * NPROJ + C_RV + h * 128 + lr * 8);
; #pragma unroll
;         for (int i = 0; i < 8; ++i) *(LAS u32x4*)(vl + (32 * hh + 4 * i + g) * 272 + lr * 16) = vv[i]; }
;     bf16x8 qf[2][4];
; #pragma unroll
;     for (int x = 0; x < 2; ++x)
; #pragma unroll
;         for (int ks = 0; ks < 4; ++ks) qf[x][ks] = *(const bf16x8*)(rowb + (size_t)(32 * ih + 16 * x + lr) * NPROJ + C_RQ + h * 128 + ks * 32 + g * 8);
;     bf16x8 pb[2][2];
;     {   f32x4 sc[4][2];
; #pragma unroll
;         for (int jt = 0; jt < 4; ++jt) {
;             bf16x8 kf[4];
; #pragma unroll
;             for (int ks = 0; ks < 4; ++ks) kf[ks] = *(const bf16x8*)(rowb + (size_t)(16 * jt + lr) * NPROJ + C_RK + h * 128 + ks * 32 + g * 8);
; #pragma unroll
;             for (int x = 0; x < 2; ++x) { sc[jt][x] = (f32x4){0.f, 0.f, 0.f, 0.f};
; #pragma unroll
;                 for (int ks = 0; ks < 4; ++ks) sc[jt][x] = MFMA16(kf[ks], qf[x][ks], sc[jt][x]); }
.LBB0_501:
	s_lshl_b32 s4, s6, 4
	s_lshl_b32 s5, s6, 6
	s_and_b32 s4, s4, 0xfffff800
	s_and_b32 s5, s5, 0x7c0
	s_or_b32 s4, s4, s5
	s_ashr_i32 s5, s4, 31
	s_lshl_b64 s[8:9], s[4:5], 14
	s_add_u32 s8, s14, s8
	s_addc_u32 s9, s15, s9
	v_lshl_add_u64 v[0:1], s[8:9], 0, v[196:197]
	s_lshl_b32 s22, s34, 8
	v_mov_b32_e32 v127, v197
	v_lshl_add_u64 v[0:1], v[0:1], 0, s[22:23]
	v_lshl_add_u64 v[32:33], v[0:1], 0, v[126:127]
	v_add_co_u32_e32 v0, vcc, s33, v32
	s_mov_b32 s5, 0x12000
	s_nop 0
	v_addc_co_u32_e32 v1, vcc, 0, v33, vcc
	v_add_co_u32_e32 v4, vcc, s5, v32
	s_mov_b32 s5, 0x22000
	s_nop 0
	v_addc_co_u32_e32 v5, vcc, 0, v33, vcc
	v_add_co_u32_e32 v8, vcc, s5, v32
	s_mov_b32 s5, 0x32000
	s_nop 0
	v_addc_co_u32_e32 v9, vcc, 0, v33, vcc
	v_add_co_u32_e32 v12, vcc, s5, v32
	s_mov_b32 s40, 0x42000
	s_nop 0
	v_addc_co_u32_e32 v13, vcc, 0, v33, vcc
	v_add_co_u32_e32 v16, vcc, s40, v32
	global_load_dwordx4 v[0:3], v[0:1], off
	s_nop 0
	v_addc_co_u32_e32 v17, vcc, 0, v33, vcc
	s_mov_b32 s5, 0x52000
	global_load_dwordx4 v[4:7], v[4:5], off
	v_add_co_u32_e32 v20, vcc, s5, v32
	global_load_dwordx4 v[8:11], v[8:9], off
	s_nop 0
	v_addc_co_u32_e32 v21, vcc, 0, v33, vcc
	s_mov_b32 s5, 0x62000
	global_load_dwordx4 v[12:15], v[12:13], off
	v_add_co_u32_e32 v24, vcc, s5, v32
	global_load_dwordx4 v[16:19], v[16:17], off
	s_nop 0
	v_addc_co_u32_e32 v25, vcc, 0, v33, vcc
	s_mov_b32 s5, 0x72000
	global_load_dwordx4 v[20:23], v[20:21], off
	v_add_co_u32_e32 v28, vcc, s5, v32
	global_load_dwordx4 v[24:27], v[24:25], off
	s_nop 0
	v_addc_co_u32_e32 v29, vcc, 0, v33, vcc
	global_load_dwordx4 v[28:31], v[28:29], off
	s_mov_b32 s5, 0x82000
	v_mov_b32_e32 v129, v197
	v_mov_b32_e32 v131, v197
	s_movk_i32 s35, 0x1000
	s_mov_b64 s[38:39], 0x1800
	v_mov_b32_e32 v105, v197
	s_ashr_i32 s7, s6, 31
	s_lshl_b64 s[6:7], s[6:7], 15
	v_lshl_add_u64 v[132:133], v[122:123], 0, s[6:7]
	s_or_b32 s6, s4, s26
	v_mov_b32_e32 v107, v197
	v_mov_b32_e32 v109, v197
	v_mov_b32_e32 v111, v197
	v_mov_b32_e32 v113, v197
	v_mov_b32_e32 v115, v197
	v_mov_b32_e32 v117, v197
	v_mov_b32_e32 v119, v197
	v_mov_b32_e32 v121, v197
	s_waitcnt vmcnt(7)
	ds_write_b128 v170, v[0:3]
	s_waitcnt vmcnt(6)
	ds_write_b128 v170, v[4:7] offset:1088
	s_waitcnt vmcnt(5)
	ds_write_b128 v170, v[8:11] offset:2176
	s_waitcnt vmcnt(4)
	ds_write_b128 v170, v[12:15] offset:3264
	s_waitcnt vmcnt(3)
	ds_write_b128 v170, v[16:19] offset:4352
	s_waitcnt vmcnt(2)
	ds_write_b128 v170, v[20:23] offset:5440
	s_waitcnt vmcnt(1)
	ds_write_b128 v170, v[24:27] offset:6528
	s_waitcnt vmcnt(0)
	ds_write_b128 v170, v[28:31] offset:7616
	v_add_co_u32_e32 v0, vcc, s5, v32
	s_mov_b32 s5, 0x92000
	s_nop 0
	v_addc_co_u32_e32 v1, vcc, 0, v33, vcc
	v_add_co_u32_e32 v4, vcc, s5, v32
	s_mov_b32 s5, 0xa2000
	s_nop 0
	v_addc_co_u32_e32 v5, vcc, 0, v33, vcc
	v_add_co_u32_e32 v8, vcc, s5, v32
	s_mov_b32 s5, 0xb2000
	s_nop 0
	v_addc_co_u32_e32 v9, vcc, 0, v33, vcc
	v_add_co_u32_e32 v12, vcc, s5, v32
	s_mov_b32 s5, 0xc2000
	s_nop 0
	v_addc_co_u32_e32 v13, vcc, 0, v33, vcc
	v_add_co_u32_e32 v16, vcc, s5, v32
	global_load_dwordx4 v[0:3], v[0:1], off
	s_nop 0
	v_addc_co_u32_e32 v17, vcc, 0, v33, vcc
	s_mov_b32 s5, 0xd2000
	global_load_dwordx4 v[4:7], v[4:5], off
	v_add_co_u32_e32 v20, vcc, s5, v32
	global_load_dwordx4 v[8:11], v[8:9], off
	s_nop 0
	v_addc_co_u32_e32 v21, vcc, 0, v33, vcc
	s_mov_b32 s5, 0xe2000
	global_load_dwordx4 v[12:15], v[12:13], off
	v_add_co_u32_e32 v24, vcc, s5, v32
	global_load_dwordx4 v[16:19], v[16:17], off
	s_nop 0
	v_addc_co_u32_e32 v25, vcc, 0, v33, vcc
	s_mov_b32 s5, 0xf2000
	global_load_dwordx4 v[20:23], v[20:21], off
	v_add_co_u32_e32 v28, vcc, s5, v32
	global_load_dwordx4 v[24:27], v[24:25], off
	s_nop 0
	v_addc_co_u32_e32 v29, vcc, 0, v33, vcc
	global_load_dwordx4 v[28:31], v[28:29], off
	s_mov_b32 s5, 0x41000
	s_waitcnt vmcnt(7)
	ds_write_b128 v170, v[0:3] offset:8704
	s_waitcnt vmcnt(6)
	ds_write_b128 v170, v[4:7] offset:9792
	s_waitcnt vmcnt(5)
	ds_write_b128 v170, v[8:11] offset:10880
	s_waitcnt vmcnt(4)
	ds_write_b128 v170, v[12:15] offset:11968
	s_waitcnt vmcnt(3)
	ds_write_b128 v170, v[16:19] offset:13056
	s_waitcnt vmcnt(2)
	ds_write_b128 v170, v[20:23] offset:14144
	s_waitcnt vmcnt(1)
	ds_write_b128 v170, v[24:27] offset:15232
	s_waitcnt vmcnt(0)
	ds_write_b128 v170, v[28:31] offset:16320
	v_lshl_add_u64 v[0:1], s[8:9], 0, v[128:129]
	v_lshl_add_u64 v[0:1], v[0:1], 0, s[22:23]
	v_lshl_add_u64 v[0:1], v[0:1], 0, v[130:131]
	v_add_co_u32_e32 v4, vcc, s35, v0
	v_lshl_add_u64 v[2:3], v[0:1], 0, s[38:39]
	s_nop 0
	v_addc_co_u32_e32 v5, vcc, 0, v1, vcc
	s_mov_b64 s[38:39], 0x41800
	v_lshl_add_u64 v[12:13], s[8:9], 0, v[104:105]
	global_load_dwordx4 v[32:35], v[4:5], off offset:2048
	global_load_dwordx4 v[28:31], v[2:3], off offset:64
	global_load_dwordx4 v[24:27], v[2:3], off offset:128
	global_load_dwordx4 v[20:23], v[2:3], off offset:192
	v_lshl_add_u64 v[2:3], v[0:1], 0, s[38:39]
	v_add_co_u32_e32 v0, vcc, s5, v0
	v_lshl_add_u64 v[12:13], v[12:13], 0, s[22:23]
	s_nop 0
	v_addc_co_u32_e32 v1, vcc, 0, v1, vcc
	v_lshl_add_u64 v[56:57], v[12:13], 0, v[130:131]
	v_add_co_u32_e32 v14, vcc, s35, v56
	s_mov_b64 s[8:9], 0x1c00
	s_nop 0
	v_addc_co_u32_e32 v15, vcc, 0, v57, vcc
	global_load_dwordx4 v[16:19], v[0:1], off offset:2048
	global_load_dwordx4 v[8:11], v[2:3], off offset:64
	global_load_dwordx4 v[4:7], v[2:3], off offset:128
	s_nop 0
	global_load_dwordx4 v[0:3], v[2:3], off offset:192
	v_lshl_add_u64 v[12:13], v[56:57], 0, s[8:9]
	global_load_dwordx4 v[36:39], v[14:15], off offset:3072
	global_load_dwordx4 v[40:43], v[12:13], off offset:64
	global_load_dwordx4 v[44:47], v[12:13], off offset:128
	global_load_dwordx4 v[48:51], v[12:13], off offset:192
	s_waitcnt vmcnt(3)
; DI unsigned pk2(float lo, float hi) { f32x2_t v = {lo, hi}; bf16x2_t b = __builtin_convertvector(v, bf16x2_t); return __builtin_bit_cast(unsigned, b); }
; DI void unpack8(const u32x4 w, float (&f)[8]) { f[0] = bflo(w.x); f[1] = bfhi(w.x); f[2] = bflo(w.y); f[3] = bfhi(w.y); f[4] = bflo(w.z); f[5] = bfhi(w.z); f[6] = bflo(w.w); f[7] = bfhi(w.w); }
; DI u32x4 pack8(const float (&f)[8]) { u32x4 w; w.x = pk2(f[0], f[1]); w.y = pk2(f[2], f[3]); w.z = pk2(f[4], f[5]); w.w = pk2(f[6], f[7]); return w; }
; DI float fexp2(float x) { return __builtin_amdgcn_exp2f(x); }
; #define MFMA16(a, b, c) __builtin_amdgcn_mfma_f32_16x16x32_bf16((a), (b), (c), 0, 0, 0)
; DI void wave_ret_out(CP p, int l, int u, int ih, int lane, LAS unsigned char* vl) {
;     ...
;         for (int jt = 0; jt < 4; ++jt) {
;             bf16x8 kf[4];
; #pragma unroll
;             for (int ks = 0; ks < 4; ++ks) kf[ks] = *(const bf16x8*)(rowb + (size_t)(16 * jt + lr) * NPROJ + C_RK + h * 128 + ks * 32 + g * 8);
; #pragma unroll
;             for (int x = 0; x < 2; ++x) { sc[jt][x] = (f32x4){0.f, 0.f, 0.f, 0.f};
; #pragma unroll
;                 for (int ks = 0; ks < 4; ++ks) sc[jt][x] = MFMA16(kf[ks], qf[x][ks], sc[jt][x]); }
;         }
; #pragma unroll
;         for (int x = 0; x < 2; ++x) { const int i = 32 * ih + 16 * x + lr;
; #pragma unroll
;             for (int jt = 0; jt < 4; ++jt)
; #pragma unroll
;                 for (int r = 0; r < 4; ++r) { const int dd = i - (16 * jt + 4 * g + r); sc[jt][x][r] *= fexp2((float)(dd < 0 ? -dd : dd) * lg); }
; #pragma unroll
;             for (int kk = 0; kk < 2; ++kk) { u32x4 w; w.x = pk2(sc[2 * kk][x][0], sc[2 * kk][x][1]); w.y = pk2(sc[2 * kk][x][2], sc[2 * kk][x][3]);
;                 w.z = pk2(sc[2 * kk + 1][x][0], sc[2 * kk + 1][x][1]); w.w = pk2(sc[2 * kk + 1][x][2], sc[2 * kk + 1][x][3]); pb[x][kk] = __builtin_bit_cast(bf16x8, w); }
;         }
;     }
; #pragma unroll
;     for (int x = 0; x < 2; ++x) { const float w = fexp2((float)(32 * ih + 16 * x + lr + 1) * lg);
; #pragma unroll
;         for (int ks = 0; ks < 4; ++ks) { float f[8]; unpack8(__builtin_bit_cast(u32x4, qf[x][ks]), f);
; #pragma unroll
;             for (int e = 0; e < 8; ++e) f[e] *= w;
;             qf[x][ks] = __builtin_bit_cast(bf16x8, pack8(f)); } }
	v_mfma_f32_16x16x32_bf16 v[12:15], v[36:39], v[32:35], 0
	s_mov_b64 s[8:9], 0x41c00
	v_mfma_f32_16x16x32_bf16 v[36:39], v[36:39], v[16:19], 0
	s_waitcnt vmcnt(2)
	v_mfma_f32_16x16x32_bf16 v[12:15], v[40:43], v[28:31], v[12:15]
	v_mfma_f32_16x16x32_bf16 v[36:39], v[40:43], v[8:11], v[36:39]
	v_add_co_u32_e32 v42, vcc, s5, v56
	v_lshl_add_u64 v[40:41], v[56:57], 0, s[8:9]
	s_waitcnt vmcnt(1)
	v_mfma_f32_16x16x32_bf16 v[12:15], v[44:47], v[24:27], v[12:15]
	v_addc_co_u32_e32 v43, vcc, 0, v57, vcc
	s_mov_b32 s5, 0x81000
	v_mfma_f32_16x16x32_bf16 v[36:39], v[44:47], v[4:7], v[36:39]
	s_mov_b64 s[8:9], 0x81c00
	s_waitcnt vmcnt(0)
	v_mfma_f32_16x16x32_bf16 v[12:15], v[48:51], v[20:23], v[12:15]
	v_mfma_f32_16x16x32_bf16 v[36:39], v[48:51], v[0:3], v[36:39]
	global_load_dwordx4 v[44:47], v[42:43], off offset:3072
	global_load_dwordx4 v[48:51], v[40:41], off offset:64
	global_load_dwordx4 v[52:55], v[40:41], off offset:128
	global_load_dwordx4 v[58:61], v[40:41], off offset:192
	s_waitcnt vmcnt(3)
	v_mfma_f32_16x16x32_bf16 v[40:43], v[44:47], v[32:35], 0
	v_mfma_f32_16x16x32_bf16 v[44:47], v[44:47], v[16:19], 0
	s_waitcnt vmcnt(2)
	v_mfma_f32_16x16x32_bf16 v[40:43], v[48:51], v[28:31], v[40:43]
	v_mfma_f32_16x16x32_bf16 v[44:47], v[48:51], v[8:11], v[44:47]
	v_add_co_u32_e32 v48, vcc, s5, v56
	s_mov_b32 s5, 0xc1000
	s_waitcnt vmcnt(1)
	v_mfma_f32_16x16x32_bf16 v[40:43], v[52:55], v[24:27], v[40:43]
	v_addc_co_u32_e32 v49, vcc, 0, v57, vcc
	v_mfma_f32_16x16x32_bf16 v[44:47], v[52:55], v[4:7], v[44:47]
	v_lshl_add_u64 v[52:53], v[56:57], 0, s[8:9]
	s_mov_b64 s[8:9], 0xc1c00
	s_waitcnt vmcnt(0)
	v_mfma_f32_16x16x32_bf16 v[40:43], v[58:61], v[20:23], v[40:43]
	v_mfma_f32_16x16x32_bf16 v[44:47], v[58:61], v[0:3], v[44:47]
	global_load_dwordx4 v[48:51], v[48:49], off offset:3072
	s_nop 0
	global_load_dwordx4 v[58:61], v[52:53], off offset:64
	global_load_dwordx4 v[62:65], v[52:53], off offset:128
	global_load_dwordx4 v[68:71], v[52:53], off offset:192
	s_waitcnt vmcnt(3)
	v_mfma_f32_16x16x32_bf16 v[52:55], v[48:51], v[32:35], 0
	v_mfma_f32_16x16x32_bf16 v[48:51], v[48:51], v[16:19], 0
	s_waitcnt vmcnt(2)
	v_mfma_f32_16x16x32_bf16 v[52:55], v[58:61], v[28:31], v[52:55]
	v_mfma_f32_16x16x32_bf16 v[48:51], v[58:61], v[8:11], v[48:51]
	s_waitcnt vmcnt(1)
	v_mfma_f32_16x16x32_bf16 v[52:55], v[62:65], v[24:27], v[52:55]
	v_mfma_f32_16x16x32_bf16 v[48:51], v[62:65], v[4:7], v[48:51]
	v_lshl_add_u64 v[64:65], v[56:57], 0, s[8:9]
	v_add_co_u32_e32 v56, vcc, s5, v56
	s_waitcnt vmcnt(0)
	v_mfma_f32_16x16x32_bf16 v[52:55], v[68:71], v[20:23], v[52:55]
	v_addc_co_u32_e32 v57, vcc, 0, v57, vcc
	s_movk_i32 s5, 0x5000
	v_mfma_f32_16x16x32_bf16 v[48:51], v[68:71], v[0:3], v[48:51]
	global_load_dwordx4 v[60:63], v[56:57], off offset:3072
	s_nop 0
	global_load_dwordx4 v[56:59], v[64:65], off offset:64
	global_load_dwordx4 v[68:71], v[64:65], off offset:128
	global_load_dwordx4 v[72:75], v[64:65], off offset:192
	s_waitcnt lgkmcnt(0)
	s_waitcnt vmcnt(3)
	v_mfma_f32_16x16x32_bf16 v[76:79], v[60:63], v[32:35], 0
	v_mfma_f32_16x16x32_bf16 v[60:63], v[60:63], v[16:19], 0
	s_waitcnt vmcnt(2)
	v_mfma_f32_16x16x32_bf16 v[76:79], v[56:59], v[28:31], v[76:79]
	v_mfma_f32_16x16x32_bf16 v[56:59], v[56:59], v[8:11], v[60:63]
	s_nop 4
	v_mul_f32_e32 v60, v66, v134
	v_mul_f32_e32 v61, v66, v135
	v_exp_f32_e32 v60, v60
	v_exp_f32_e32 v61, v61
	s_waitcnt vmcnt(1)
	v_mfma_f32_16x16x32_bf16 v[56:59], v[68:71], v[4:7], v[56:59]
	v_mul_f32_e64 v12, v60, v12
	v_mul_f32_e64 v13, v61, v13
	v_mul_f32_e32 v61, v66, v136
	v_exp_f32_e32 v62, v61
	v_mul_f32_e32 v61, v66, v137
	v_exp_f32_e32 v63, v61
	v_mul_f32_e32 v61, v66, v138
	v_cvt_pk_bf16_f32 v12, v12, v13
	s_waitcnt vmcnt(0)
	v_mfma_f32_16x16x32_bf16 v[56:59], v[72:75], v[0:3], v[56:59]
	v_mul_f32_e64 v14, v62, v14
	v_mul_f32_e64 v15, v63, v15
	v_exp_f32_e32 v62, v61
	v_mul_f32_e32 v61, v66, v139
	v_exp_f32_e32 v63, v61
	v_mul_f32_e32 v61, v66, v143
	v_cvt_pk_bf16_f32 v13, v14, v15
	v_mfma_f32_16x16x32_bf16 v[76:79], v[68:71], v[24:27], v[76:79]
	v_mul_f32_e64 v40, v62, v40
	v_mul_f32_e64 v41, v63, v41
	v_exp_f32_e32 v62, v61
	v_mul_f32_e32 v61, v66, v144
	v_exp_f32_e32 v63, v61
	v_mul_f32_e32 v61, v66, v145
	v_cvt_pk_bf16_f32 v14, v40, v41
	v_mfma_f32_16x16x32_bf16 v[76:79], v[72:75], v[20:23], v[76:79]
	v_mul_f32_e64 v42, v62, v42
	v_mul_f32_e64 v43, v63, v43
	v_exp_f32_e32 v62, v61
	v_mul_f32_e32 v61, v66, v146
	v_exp_f32_e32 v63, v61
	v_mul_f32_e32 v61, v66, v147
	v_cvt_pk_bf16_f32 v15, v42, v43
	v_pk_mul_f32 v[52:53], v[62:63], v[52:53]
	s_nop 0
	v_cvt_pk_bf16_f32 v40, v52, v53
	v_mul_f32_e32 v52, v66, v153
	v_mul_f32_e32 v53, v66, v154
	v_exp_f32_e32 v52, v52
	v_exp_f32_e32 v53, v53
	v_exp_f32_e32 v62, v61
	v_mul_f32_e32 v61, v66, v148
	v_exp_f32_e32 v63, v61
	v_pk_mul_f32 v[36:37], v[52:53], v[36:37]
	v_mul_f32_e32 v52, v66, v155
	v_mul_f32_e32 v53, v66, v156
	v_exp_f32_e32 v52, v52
	v_exp_f32_e32 v53, v53
	v_mul_f32_e32 v61, v66, v149
	v_pk_mul_f32 v[54:55], v[62:63], v[54:55]
	v_exp_f32_e32 v62, v61
	v_mul_f32_e32 v61, v66, v150
	v_exp_f32_e32 v63, v61
	v_mul_f32_e32 v61, v66, v151
	v_exp_f32_e32 v64, v61
	v_mul_f32_e32 v61, v66, v152
	v_pk_mul_f32 v[38:39], v[52:53], v[38:39]
	v_mul_f32_e32 v52, v66, v157
	v_exp_f32_e32 v65, v61
	v_exp_f32_e32 v61, v52
	v_cvt_pk_bf16_f32 v41, v54, v55
	v_pk_mul_f32 v[62:63], v[62:63], v[76:77]
	v_pk_mul_f32 v[64:65], v[64:65], v[78:79]
	v_pk_mul_f32 v[52:53], v[60:61], v[44:45]
	v_mul_f32_e32 v44, v66, v158
	v_mul_f32_e32 v45, v66, v159
	v_exp_f32_e32 v44, v44
	v_exp_f32_e32 v45, v45
	v_cvt_pk_bf16_f32 v42, v62, v63
	v_cvt_pk_bf16_f32 v43, v64, v65
	v_pk_mul_f32 v[54:55], v[44:45], v[46:47]
; #define LAS __attribute__((address_space(3)))
; DI unsigned pk2(float lo, float hi) { f32x2_t v = {lo, hi}; bf16x2_t b = __builtin_convertvector(v, bf16x2_t); return __builtin_bit_cast(unsigned, b); }
; DI void unpack8(const u32x4 w, float (&f)[8]) { f[0] = bflo(w.x); f[1] = bfhi(w.x); f[2] = bflo(w.y); f[3] = bfhi(w.y); f[4] = bflo(w.z); f[5] = bfhi(w.z); f[6] = bflo(w.w); f[7] = bfhi(w.w); }
; DI float fexp2(float x) { return __builtin_amdgcn_exp2f(x); }
; DI void wave_ret_out(CP p, int l, int u, int ih, int lane, LAS unsigned char* vl) {
;     ...
; #pragma unroll
;         for (int x = 0; x < 2; ++x) { const int i = 32 * ih + 16 * x + lr;
; #pragma unroll
;             for (int jt = 0; jt < 4; ++jt)
; #pragma unroll
;                 for (int r = 0; r < 4; ++r) { const int dd = i - (16 * jt + 4 * g + r); sc[jt][x][r] *= fexp2((float)(dd < 0 ? -dd : dd) * lg); }
; #pragma unroll
;             for (int kk = 0; kk < 2; ++kk) { u32x4 w; w.x = pk2(sc[2 * kk][x][0], sc[2 * kk][x][1]); w.y = pk2(sc[2 * kk][x][2], sc[2 * kk][x][3]);
;                 w.z = pk2(sc[2 * kk + 1][x][0], sc[2 * kk + 1][x][1]); w.w = pk2(sc[2 * kk + 1][x][2], sc[2 * kk + 1][x][3]); pb[x][kk] = __builtin_bit_cast(bf16x8, w); }
;         }
;     }
; #pragma unroll
;     for (int x = 0; x < 2; ++x) { const float w = fexp2((float)(32 * ih + 16 * x + lr + 1) * lg);
; #pragma unroll
;         for (int ks = 0; ks < 4; ++ks) { float f[8]; unpack8(__builtin_bit_cast(u32x4, qf[x][ks]), f);
; #pragma unroll
;             for (int e = 0; e < 8; ++e) f[e] *= w;
;             qf[x][ks] = __builtin_bit_cast(bf16x8, pack8(f)); } }
;     f32x4 acc[8][2];
;     LDS_WAIT();
;     const bf16* rst = (const bf16*)(p->ws + WS_RST) + (size_t)u * 16384;
; #pragma unroll
;     for (int et = 0; et < 8; ++et) {
;         const int e = 16 * et + lr;
;         bf16x8 va[2], ra[4];
; #pragma unroll
;         for (int kk = 0; kk < 2; ++kk) { const LAS unsigned char* vp_ = vl + (32 * kk + 4 * g + (lr >> 2)) * 272 + et * 32 + 8 * (lr & 3);
;             const v4i16_t lo = __builtin_amdgcn_ds_read_tr16_b64_v4i16((LAS v4i16_t*)vp_), hi = __builtin_amdgcn_ds_read_tr16_b64_v4i16((LAS v4i16_t*)(vp_ + 16 * 272));
;             va[kk] = (bf16x8){lo[0], lo[1], lo[2], lo[3], hi[0], hi[1], hi[2], hi[3]}; }
; #pragma unroll
;         for (int ks = 0; ks < 4; ++ks) ra[ks] = *(const bf16x8*)(rst + (size_t)e * 128 + ks * 32 + g * 8);
	v_mul_f32_e32 v44, v66, v160
	v_mul_f32_e32 v45, v66, v161
	v_exp_f32_e32 v44, v44
	v_exp_f32_e32 v45, v45
	v_cvt_pk_bf16_f32 v47, v54, v55
	v_cvt_pk_bf16_f32 v46, v52, v53
	v_pk_mul_f32 v[48:49], v[44:45], v[48:49]
	v_mul_f32_e32 v44, v66, v162
	v_mul_f32_e32 v45, v66, v163
	v_exp_f32_e32 v44, v44
	v_exp_f32_e32 v45, v45
	v_cvt_pk_bf16_f32 v52, v48, v49
	v_lshlrev_b32_e32 v48, 16, v34
	v_and_b32_e32 v49, 0xffff0000, v34
	v_pk_mul_f32 v[50:51], v[44:45], v[50:51]
	v_mul_f32_e32 v44, v66, v164
	v_mul_f32_e32 v45, v66, v165
	v_exp_f32_e32 v44, v44
	v_exp_f32_e32 v45, v45
	v_lshlrev_b32_e32 v34, 16, v35
	v_and_b32_e32 v35, 0xffff0000, v35
	v_cvt_pk_bf16_f32 v53, v50, v51
	v_pk_mul_f32 v[56:57], v[44:45], v[56:57]
	v_mul_f32_e32 v44, v66, v166
	v_mul_f32_e32 v45, v66, v167
	v_exp_f32_e32 v44, v44
	v_exp_f32_e32 v45, v45
	v_cvt_pk_bf16_f32 v54, v56, v57
	v_pk_mul_f32 v[58:59], v[44:45], v[58:59]
	v_cvt_pk_bf16_f32 v44, v36, v37
	v_mul_f32_e32 v36, v66, v168
	v_exp_f32_e32 v36, v36
	v_cvt_pk_bf16_f32 v45, v38, v39
	v_lshlrev_b32_e32 v38, 16, v32
	v_and_b32_e32 v39, 0xffff0000, v32
	v_lshlrev_b32_e32 v32, 16, v33
	v_and_b32_e32 v33, 0xffff0000, v33
	v_pk_mul_f32 v[32:33], v[36:37], v[32:33] op_sel_hi:[0,1]
	v_cvt_pk_bf16_f32 v57, v32, v33
	v_lshlrev_b32_e32 v32, 16, v28
	v_and_b32_e32 v33, 0xffff0000, v28
	v_lshlrev_b32_e32 v28, 16, v29
	v_and_b32_e32 v29, 0xffff0000, v29
	v_pk_mul_f32 v[28:29], v[36:37], v[28:29] op_sel_hi:[0,1]
	v_cvt_pk_bf16_f32 v69, v28, v29
	v_lshlrev_b32_e32 v28, 16, v24
	v_and_b32_e32 v29, 0xffff0000, v24
	v_lshlrev_b32_e32 v24, 16, v25
	v_and_b32_e32 v25, 0xffff0000, v25
	v_pk_mul_f32 v[34:35], v[36:37], v[34:35] op_sel_hi:[0,1]
	v_pk_mul_f32 v[24:25], v[36:37], v[24:25] op_sel_hi:[0,1]
	v_cvt_pk_bf16_f32 v55, v58, v59
	v_cvt_pk_bf16_f32 v59, v34, v35
	v_lshlrev_b32_e32 v34, 16, v30
	v_and_b32_e32 v35, 0xffff0000, v30
	v_lshlrev_b32_e32 v30, 16, v31
	v_and_b32_e32 v31, 0xffff0000, v31
	v_cvt_pk_bf16_f32 v73, v24, v25
	v_lshlrev_b32_e32 v24, 16, v20
	v_and_b32_e32 v25, 0xffff0000, v20
	v_lshlrev_b32_e32 v20, 16, v21
	v_and_b32_e32 v21, 0xffff0000, v21
	v_pk_mul_f32 v[30:31], v[36:37], v[30:31] op_sel_hi:[0,1]
	v_pk_mul_f32 v[20:21], v[36:37], v[20:21] op_sel_hi:[0,1]
	v_cvt_pk_bf16_f32 v71, v30, v31
	v_lshlrev_b32_e32 v30, 16, v26
	v_and_b32_e32 v31, 0xffff0000, v26
	v_lshlrev_b32_e32 v26, 16, v27
	v_and_b32_e32 v27, 0xffff0000, v27
	v_cvt_pk_bf16_f32 v77, v20, v21
	v_mul_f32_e32 v20, v66, v169
	v_pk_mul_f32 v[26:27], v[36:37], v[26:27] op_sel_hi:[0,1]
	v_exp_f32_e32 v20, v20
	v_cvt_pk_bf16_f32 v75, v26, v27
	v_lshlrev_b32_e32 v26, 16, v22
	v_and_b32_e32 v27, 0xffff0000, v22
	v_lshlrev_b32_e32 v22, 16, v23
	v_and_b32_e32 v23, 0xffff0000, v23
	v_pk_mul_f32 v[24:25], v[36:37], v[24:25] op_sel_hi:[0,1]
	v_pk_mul_f32 v[22:23], v[36:37], v[22:23] op_sel_hi:[0,1]
	v_cvt_pk_bf16_f32 v76, v24, v25
	v_cvt_pk_bf16_f32 v79, v22, v23
	v_lshlrev_b32_e32 v22, 16, v16
	v_and_b32_e32 v23, 0xffff0000, v16
	v_lshlrev_b32_e32 v16, 16, v17
	v_and_b32_e32 v17, 0xffff0000, v17
	v_lshlrev_b32_e32 v24, 16, v18
	v_and_b32_e32 v25, 0xffff0000, v18
	v_lshlrev_b32_e32 v18, 16, v19
	v_and_b32_e32 v19, 0xffff0000, v19
	v_pk_mul_f32 v[16:17], v[20:21], v[16:17] op_sel_hi:[0,1]
	v_pk_mul_f32 v[18:19], v[20:21], v[18:19] op_sel_hi:[0,1]
	v_cvt_pk_bf16_f32 v81, v16, v17
	v_cvt_pk_bf16_f32 v83, v18, v19
	v_lshlrev_b32_e32 v16, 16, v8
	v_and_b32_e32 v17, 0xffff0000, v8
	v_lshlrev_b32_e32 v8, 16, v9
	v_and_b32_e32 v9, 0xffff0000, v9
	v_lshlrev_b32_e32 v18, 16, v10
	v_and_b32_e32 v19, 0xffff0000, v10
	v_lshlrev_b32_e32 v10, 16, v11
	v_and_b32_e32 v11, 0xffff0000, v11
	v_pk_mul_f32 v[8:9], v[20:21], v[8:9] op_sel_hi:[0,1]
	v_pk_mul_f32 v[10:11], v[20:21], v[10:11] op_sel_hi:[0,1]
	v_cvt_pk_bf16_f32 v85, v8, v9
	v_cvt_pk_bf16_f32 v87, v10, v11
	v_lshlrev_b32_e32 v8, 16, v4
	v_and_b32_e32 v9, 0xffff0000, v4
	v_lshlrev_b32_e32 v4, 16, v5
	v_and_b32_e32 v5, 0xffff0000, v5
	v_lshlrev_b32_e32 v10, 16, v6
	v_and_b32_e32 v11, 0xffff0000, v6
	v_lshlrev_b32_e32 v6, 16, v7
	v_and_b32_e32 v7, 0xffff0000, v7
	v_pk_mul_f32 v[4:5], v[20:21], v[4:5] op_sel_hi:[0,1]
	v_pk_mul_f32 v[6:7], v[20:21], v[6:7] op_sel_hi:[0,1]
	v_cvt_pk_bf16_f32 v93, v4, v5
	v_cvt_pk_bf16_f32 v95, v6, v7
	v_lshlrev_b32_e32 v4, 16, v0
	v_and_b32_e32 v5, 0xffff0000, v0
	v_lshlrev_b32_e32 v0, 16, v1
	v_and_b32_e32 v1, 0xffff0000, v1
	v_lshlrev_b32_e32 v6, 16, v2
	v_and_b32_e32 v7, 0xffff0000, v2
	v_lshlrev_b32_e32 v2, 16, v3
	v_and_b32_e32 v3, 0xffff0000, v3
	v_pk_mul_f32 v[28:29], v[36:37], v[28:29] op_sel_hi:[0,1]
	v_pk_mul_f32 v[26:27], v[36:37], v[26:27] op_sel_hi:[0,1]
	v_pk_mul_f32 v[22:23], v[20:21], v[22:23] op_sel_hi:[0,1]
	v_pk_mul_f32 v[24:25], v[20:21], v[24:25] op_sel_hi:[0,1]
	v_pk_mul_f32 v[16:17], v[20:21], v[16:17] op_sel_hi:[0,1]
	v_pk_mul_f32 v[18:19], v[20:21], v[18:19] op_sel_hi:[0,1]
	v_pk_mul_f32 v[8:9], v[20:21], v[8:9] op_sel_hi:[0,1]
	v_pk_mul_f32 v[10:11], v[20:21], v[10:11] op_sel_hi:[0,1]
	v_pk_mul_f32 v[4:5], v[20:21], v[4:5] op_sel_hi:[0,1]
	v_pk_mul_f32 v[0:1], v[20:21], v[0:1] op_sel_hi:[0,1]
	v_pk_mul_f32 v[6:7], v[20:21], v[6:7] op_sel_hi:[0,1]
	v_pk_mul_f32 v[2:3], v[20:21], v[2:3] op_sel_hi:[0,1]
	v_cvt_pk_bf16_f32 v72, v28, v29
	v_cvt_pk_bf16_f32 v78, v26, v27
	v_cvt_pk_bf16_f32 v80, v22, v23
	v_cvt_pk_bf16_f32 v82, v24, v25
	v_cvt_pk_bf16_f32 v84, v16, v17
	v_cvt_pk_bf16_f32 v86, v18, v19
	v_cvt_pk_bf16_f32 v92, v8, v9
	v_cvt_pk_bf16_f32 v94, v10, v11
	v_cvt_pk_bf16_f32 v96, v4, v5
	v_cvt_pk_bf16_f32 v97, v0, v1
	v_cvt_pk_bf16_f32 v98, v6, v7
	v_cvt_pk_bf16_f32 v99, v2, v3
	ds_read_b64_tr_b16 v[2:3], v171 offset:4352
	ds_read_b64_tr_b16 v[0:1], v171
	ds_read_b64_tr_b16 v[16:17], v171 offset:32
	ds_read_b64_tr_b16 v[4:5], v171 offset:8704
	ds_read_b64_tr_b16 v[6:7], v171 offset:13056
	global_load_dwordx4 v[8:11], v[132:133], off
	global_load_dwordx4 v[18:21], v[132:133], off offset:64
	global_load_dwordx4 v[22:25], v[132:133], off offset:128
	global_load_dwordx4 v[26:29], v[132:133], off offset:192
	v_pk_mul_f32 v[32:33], v[36:37], v[32:33] op_sel_hi:[0,1]
	v_pk_mul_f32 v[30:31], v[36:37], v[30:31] op_sel_hi:[0,1]
	v_cvt_pk_bf16_f32 v68, v32, v33
	v_cvt_pk_bf16_f32 v74, v30, v31
	s_waitcnt lgkmcnt(3)
; #define LAS __attribute__((address_space(3)))
; #define MFMA16(a, b, c) __builtin_amdgcn_mfma_f32_16x16x32_bf16((a), (b), (c), 0, 0, 0)
; DI void wave_ret_out(CP p, int l, int u, int ih, int lane, LAS unsigned char* vl) {
;     ...
; #pragma unroll
;     for (int et = 0; et < 8; ++et) {
;         const int e = 16 * et + lr;
;         bf16x8 va[2], ra[4];
; #pragma unroll
;         for (int kk = 0; kk < 2; ++kk) { const LAS unsigned char* vp_ = vl + (32 * kk + 4 * g + (lr >> 2)) * 272 + et * 32 + 8 * (lr & 3);
;             const v4i16_t lo = __builtin_amdgcn_ds_read_tr16_b64_v4i16((LAS v4i16_t*)vp_), hi = __builtin_amdgcn_ds_read_tr16_b64_v4i16((LAS v4i16_t*)(vp_ + 16 * 272));
;             va[kk] = (bf16x8){lo[0], lo[1], lo[2], lo[3], hi[0], hi[1], hi[2], hi[3]}; }
; #pragma unroll
;         for (int ks = 0; ks < 4; ++ks) ra[ks] = *(const bf16x8*)(rst + (size_t)e * 128 + ks * 32 + g * 8);
; #pragma unroll
;         for (int x = 0; x < 2; ++x) { f32x4 a = {0.f, 0.f, 0.f, 0.f};
; #pragma unroll
;             for (int kk = 0; kk < 2; ++kk) a = MFMA16(va[kk], pb[x][kk], a);
; #pragma unroll
;             for (int ks = 0; ks < 4; ++ks) a = MFMA16(ra[ks], qf[x][ks], a);
;             acc[et][x] = a; }
;     }
	v_mfma_f32_16x16x32_bf16 v[30:33], v[0:3], v[12:15], 0
	v_mul_f32_e64 v38, v36, v38
	v_mul_f32_e64 v39, v36, v39
	v_pk_mul_f32 v[48:49], v[36:37], v[48:49] op_sel_hi:[0,1]
	v_cvt_pk_bf16_f32 v56, v38, v39
	v_mfma_f32_16x16x32_bf16 v[0:3], v[0:3], v[44:47], 0
	v_cvt_pk_bf16_f32 v58, v48, v49
	v_pk_mul_f32 v[34:35], v[36:37], v[34:35] op_sel_hi:[0,1]
	v_cvt_pk_bf16_f32 v70, v34, v35
	s_waitcnt lgkmcnt(0)
	v_mfma_f32_16x16x32_bf16 v[30:33], v[4:7], v[40:43], v[30:33]
	v_mfma_f32_16x16x32_bf16 v[0:3], v[4:7], v[52:55], v[0:3]
	s_waitcnt vmcnt(3)
	v_mfma_f32_16x16x32_bf16 v[30:33], v[8:11], v[56:59], v[30:33]
	v_mfma_f32_16x16x32_bf16 v[0:3], v[8:11], v[80:83], v[0:3]
	v_add_co_u32_e32 v10, vcc, s35, v132
	s_waitcnt vmcnt(2)
	v_mfma_f32_16x16x32_bf16 v[30:33], v[18:21], v[68:71], v[30:33]
	v_addc_co_u32_e32 v11, vcc, 0, v133, vcc
	v_add_co_u32_e32 v8, vcc, s33, v132
	v_mfma_f32_16x16x32_bf16 v[0:3], v[18:21], v[84:87], v[0:3]
	s_nop 0
	v_addc_co_u32_e32 v9, vcc, 0, v133, vcc
	v_add_co_u32_e32 v64, vcc, s77, v132
	s_waitcnt vmcnt(1)
	v_mfma_f32_16x16x32_bf16 v[30:33], v[22:25], v[72:75], v[30:33]
	v_addc_co_u32_e32 v65, vcc, 0, v133, vcc
	v_add_co_u32_e32 v172, vcc, s19, v132
	v_mfma_f32_16x16x32_bf16 v[0:3], v[22:25], v[92:95], v[0:3]
	s_nop 0
	v_addc_co_u32_e32 v173, vcc, 0, v133, vcc
	s_waitcnt vmcnt(0)
	v_mfma_f32_16x16x32_bf16 v[36:39], v[26:29], v[76:79], v[30:33]
	v_mfma_f32_16x16x32_bf16 v[4:7], v[26:29], v[96:99], v[0:3]
	ds_read_b64_tr_b16 v[18:19], v171 offset:4384
	s_nop 1
	ds_read_b64_tr_b16 v[0:1], v171 offset:8736
	ds_read_b64_tr_b16 v[2:3], v171 offset:13088
	global_load_dwordx4 v[20:23], v[8:9], off offset:-4096
	global_load_dwordx4 v[24:27], v[10:11], off offset:64
	global_load_dwordx4 v[28:31], v[10:11], off offset:128
	global_load_dwordx4 v[48:51], v[10:11], off offset:192
	s_waitcnt lgkmcnt(2)
	v_mfma_f32_16x16x32_bf16 v[32:35], v[16:19], v[12:15], 0
	v_mfma_f32_16x16x32_bf16 v[16:19], v[16:19], v[44:47], 0
	s_waitcnt lgkmcnt(0)
	v_mfma_f32_16x16x32_bf16 v[32:35], v[0:3], v[40:43], v[32:35]
	v_mfma_f32_16x16x32_bf16 v[0:3], v[0:3], v[52:55], v[16:19]
	s_waitcnt vmcnt(3)
	v_mfma_f32_16x16x32_bf16 v[32:35], v[20:23], v[56:59], v[32:35]
	v_mfma_f32_16x16x32_bf16 v[0:3], v[20:23], v[80:83], v[0:3]
	s_nop 1
	ds_read_b64_tr_b16 v[16:17], v171 offset:64
	ds_read_b64_tr_b16 v[18:19], v171 offset:4416
	ds_read_b64_tr_b16 v[20:21], v171 offset:8768
	ds_read_b64_tr_b16 v[22:23], v171 offset:13120
	s_waitcnt vmcnt(2)
	v_mfma_f32_16x16x32_bf16 v[32:35], v[24:27], v[68:71], v[32:35]
	v_mfma_f32_16x16x32_bf16 v[0:3], v[24:27], v[84:87], v[0:3]
	s_waitcnt vmcnt(1)
	v_mfma_f32_16x16x32_bf16 v[32:35], v[28:31], v[72:75], v[32:35]
	v_mfma_f32_16x16x32_bf16 v[0:3], v[28:31], v[92:95], v[0:3]
	global_load_dwordx4 v[24:27], v[8:9], off
	global_load_dwordx4 v[28:31], v[8:9], off offset:64
	global_load_dwordx4 v[60:63], v[8:9], off offset:128
	s_nop 0
	global_load_dwordx4 v[8:11], v[8:9], off offset:192
	s_waitcnt vmcnt(4)
	v_mfma_f32_16x16x32_bf16 v[32:35], v[48:51], v[76:79], v[32:35]
	v_mfma_f32_16x16x32_bf16 v[0:3], v[48:51], v[96:99], v[0:3]
	s_waitcnt lgkmcnt(2)
	v_mfma_f32_16x16x32_bf16 v[48:51], v[16:19], v[12:15], 0
	v_mfma_f32_16x16x32_bf16 v[16:19], v[16:19], v[44:47], 0
	s_waitcnt lgkmcnt(0)
	v_mfma_f32_16x16x32_bf16 v[48:51], v[20:23], v[40:43], v[48:51]
	v_mfma_f32_16x16x32_bf16 v[16:19], v[20:23], v[52:55], v[16:19]
	s_waitcnt vmcnt(3)
	v_mfma_f32_16x16x32_bf16 v[48:51], v[24:27], v[56:59], v[48:51]
	v_mfma_f32_16x16x32_bf16 v[16:19], v[24:27], v[80:83], v[16:19]
	s_waitcnt vmcnt(2)
	v_mfma_f32_16x16x32_bf16 v[48:51], v[28:31], v[68:71], v[48:51]
	v_mfma_f32_16x16x32_bf16 v[16:19], v[28:31], v[84:87], v[16:19]
	s_waitcnt vmcnt(1)
	v_mfma_f32_16x16x32_bf16 v[48:51], v[60:63], v[72:75], v[48:51]
	v_mfma_f32_16x16x32_bf16 v[16:19], v[60:63], v[92:95], v[16:19]
	s_waitcnt vmcnt(0)
	v_mfma_f32_16x16x32_bf16 v[48:51], v[8:11], v[76:79], v[48:51]
	v_mfma_f32_16x16x32_bf16 v[8:11], v[8:11], v[96:99], v[16:19]
	s_nop 4
	ds_read_b64_tr_b16 v[16:17], v171 offset:96
	ds_read_b64_tr_b16 v[18:19], v171 offset:4448
	ds_read_b64_tr_b16 v[20:21], v171 offset:8800
	ds_read_b64_tr_b16 v[22:23], v171 offset:13152
	global_load_dwordx4 v[24:27], v[172:173], off offset:-4096
	global_load_dwordx4 v[28:31], v[64:65], off offset:64
	global_load_dwordx4 v[60:63], v[64:65], off offset:128
	s_nop 0
	global_load_dwordx4 v[64:67], v[64:65], off offset:192
	s_waitcnt lgkmcnt(2)
	v_mfma_f32_16x16x32_bf16 v[88:91], v[16:19], v[12:15], 0
	v_mfma_f32_16x16x32_bf16 v[16:19], v[16:19], v[44:47], 0
	s_waitcnt lgkmcnt(0)
	v_mfma_f32_16x16x32_bf16 v[88:91], v[20:23], v[40:43], v[88:91]
	v_mfma_f32_16x16x32_bf16 v[16:19], v[20:23], v[52:55], v[16:19]
	s_waitcnt vmcnt(3)
	v_mfma_f32_16x16x32_bf16 v[88:91], v[24:27], v[56:59], v[88:91]
	v_mfma_f32_16x16x32_bf16 v[16:19], v[24:27], v[80:83], v[16:19]
	s_waitcnt vmcnt(2)
	v_mfma_f32_16x16x32_bf16 v[88:91], v[28:31], v[68:71], v[88:91]
	v_mfma_f32_16x16x32_bf16 v[16:19], v[28:31], v[84:87], v[16:19]
	s_waitcnt vmcnt(1)
	v_mfma_f32_16x16x32_bf16 v[88:91], v[60:63], v[72:75], v[88:91]
	v_mfma_f32_16x16x32_bf16 v[16:19], v[60:63], v[92:95], v[16:19]
	s_waitcnt vmcnt(0)
	v_mfma_f32_16x16x32_bf16 v[100:103], v[64:67], v[76:79], v[88:91]
	v_mfma_f32_16x16x32_bf16 v[28:31], v[64:67], v[96:99], v[16:19]
	s_nop 4
	ds_read_b64_tr_b16 v[16:17], v171 offset:128
	ds_read_b64_tr_b16 v[18:19], v171 offset:4480
	ds_read_b64_tr_b16 v[20:21], v171 offset:8832
	ds_read_b64_tr_b16 v[22:23], v171 offset:13184
	global_load_dwordx4 v[24:27], v[172:173], off
	global_load_dwordx4 v[60:63], v[172:173], off offset:64
	global_load_dwordx4 v[64:67], v[172:173], off offset:128
	s_nop 0
	global_load_dwordx4 v[172:175], v[172:173], off offset:192
	s_waitcnt lgkmcnt(2)
; #define LAS __attribute__((address_space(3)))
; #define MFMA16(a, b, c) __builtin_amdgcn_mfma_f32_16x16x32_bf16((a), (b), (c), 0, 0, 0)
; template <bool GROUPNORM>
; DI void wave_tail(f32x4 (&acc)[8][2], int lane, const float* gain, const bf16* gate0, bf16* out0, size_t gate_stride) {
;     const int g = lane >> 4, lr = lane & 15;
; #pragma unroll
;     for (int x = 0; x < 2; ++x) {
;         u32x2 gws[8];
; #pragma unroll
;         for (int et = 0; et < 8; ++et) gws[et] = *(const u32x2*)(gate0 + (size_t)(16 * x + lr) * gate_stride + 16 * et + 4 * g);
; DI void wave_ret_out(CP p, int l, int u, int ih, int lane, LAS unsigned char* vl) {
;     ...
; #pragma unroll
;     for (int et = 0; et < 8; ++et) {
;         const int e = 16 * et + lr;
;         bf16x8 va[2], ra[4];
; #pragma unroll
;         for (int kk = 0; kk < 2; ++kk) { const LAS unsigned char* vp_ = vl + (32 * kk + 4 * g + (lr >> 2)) * 272 + et * 32 + 8 * (lr & 3);
;             const v4i16_t lo = __builtin_amdgcn_ds_read_tr16_b64_v4i16((LAS v4i16_t*)vp_), hi = __builtin_amdgcn_ds_read_tr16_b64_v4i16((LAS v4i16_t*)(vp_ + 16 * 272));
;             va[kk] = (bf16x8){lo[0], lo[1], lo[2], lo[3], hi[0], hi[1], hi[2], hi[3]}; }
; #pragma unroll
;         for (int ks = 0; ks < 4; ++ks) ra[ks] = *(const bf16x8*)(rst + (size_t)e * 128 + ks * 32 + g * 8);
; #pragma unroll
;         for (int x = 0; x < 2; ++x) { f32x4 a = {0.f, 0.f, 0.f, 0.f};
; #pragma unroll
;             for (int kk = 0; kk < 2; ++kk) a = MFMA16(va[kk], pb[x][kk], a);
; #pragma unroll
;             for (int ks = 0; ks < 4; ++ks) a = MFMA16(ra[ks], qf[x][ks], a);
;             acc[et][x] = a; }
;     }
;     const int tokh = tok0 + 32 * ih;
;     wave_tail<true>(acc, lane, p->ret_norm_g + l * 512 + h * 128, proj + (size_t)tokh * NPROJ + C_RG + h * 128, (bf16*)(p->ws + WS_BR) + (size_t)tokh * 512 + h * 128, NPROJ);
	v_mfma_f32_16x16x32_bf16 v[88:91], v[16:19], v[12:15], 0
	v_mfma_f32_16x16x32_bf16 v[16:19], v[16:19], v[44:47], 0
	s_waitcnt lgkmcnt(0)
	v_mfma_f32_16x16x32_bf16 v[88:91], v[20:23], v[40:43], v[88:91]
	v_mfma_f32_16x16x32_bf16 v[16:19], v[20:23], v[52:55], v[16:19]
	s_waitcnt vmcnt(3)
	v_mfma_f32_16x16x32_bf16 v[88:91], v[24:27], v[56:59], v[88:91]
	v_mfma_f32_16x16x32_bf16 v[16:19], v[24:27], v[80:83], v[16:19]
	s_waitcnt vmcnt(2)
	v_mfma_f32_16x16x32_bf16 v[88:91], v[60:63], v[68:71], v[88:91]
	v_mfma_f32_16x16x32_bf16 v[16:19], v[60:63], v[84:87], v[16:19]
	s_waitcnt vmcnt(1)
	v_mfma_f32_16x16x32_bf16 v[88:91], v[64:67], v[72:75], v[88:91]
	v_mfma_f32_16x16x32_bf16 v[16:19], v[64:67], v[92:95], v[16:19]
	v_add_co_u32_e32 v64, vcc, s5, v132
	s_nop 1
	v_addc_co_u32_e32 v65, vcc, 0, v133, vcc
	v_add_co_u32_e32 v188, vcc, s11, v132
	s_waitcnt vmcnt(0)
	v_mfma_f32_16x16x32_bf16 v[88:91], v[172:175], v[76:79], v[88:91]
	v_addc_co_u32_e32 v189, vcc, 0, v133, vcc
	v_add_co_u32_e32 v132, vcc, s80, v132
	v_mfma_f32_16x16x32_bf16 v[24:27], v[172:175], v[96:99], v[16:19]
	s_nop 2
	ds_read_b64_tr_b16 v[16:17], v171 offset:160
	ds_read_b64_tr_b16 v[18:19], v171 offset:4512
	ds_read_b64_tr_b16 v[20:21], v171 offset:8864
	ds_read_b64_tr_b16 v[22:23], v171 offset:13216
	global_load_dwordx4 v[60:63], v[188:189], off offset:-4096
	global_load_dwordx4 v[172:175], v[64:65], off offset:64
	global_load_dwordx4 v[176:179], v[64:65], off offset:128
	global_load_dwordx4 v[180:183], v[64:65], off offset:192
	v_addc_co_u32_e32 v133, vcc, 0, v133, vcc
	s_waitcnt lgkmcnt(2)
	v_mfma_f32_16x16x32_bf16 v[64:67], v[16:19], v[12:15], 0
	v_mfma_f32_16x16x32_bf16 v[16:19], v[16:19], v[44:47], 0
	s_waitcnt lgkmcnt(0)
	v_mfma_f32_16x16x32_bf16 v[64:67], v[20:23], v[40:43], v[64:67]
	v_mfma_f32_16x16x32_bf16 v[16:19], v[20:23], v[52:55], v[16:19]
	s_waitcnt vmcnt(3)
	v_mfma_f32_16x16x32_bf16 v[64:67], v[60:63], v[56:59], v[64:67]
	v_mfma_f32_16x16x32_bf16 v[16:19], v[60:63], v[80:83], v[16:19]
	s_waitcnt vmcnt(2)
	v_mfma_f32_16x16x32_bf16 v[64:67], v[172:175], v[68:71], v[64:67]
	v_mfma_f32_16x16x32_bf16 v[16:19], v[172:175], v[84:87], v[16:19]
	s_waitcnt vmcnt(1)
	v_mfma_f32_16x16x32_bf16 v[64:67], v[176:179], v[72:75], v[64:67]
	v_mfma_f32_16x16x32_bf16 v[16:19], v[176:179], v[92:95], v[16:19]
	s_waitcnt vmcnt(0)
	v_mfma_f32_16x16x32_bf16 v[64:67], v[180:183], v[76:79], v[64:67]
	v_mfma_f32_16x16x32_bf16 v[20:23], v[180:183], v[96:99], v[16:19]
	s_nop 4
	ds_read_b64_tr_b16 v[16:17], v171 offset:192
	ds_read_b64_tr_b16 v[18:19], v171 offset:4544
	ds_read_b64_tr_b16 v[172:173], v171 offset:8896
	ds_read_b64_tr_b16 v[174:175], v171 offset:13248
	global_load_dwordx4 v[176:179], v[188:189], off
	global_load_dwordx4 v[180:183], v[188:189], off offset:64
	global_load_dwordx4 v[184:187], v[188:189], off offset:128
	s_nop 0
	global_load_dwordx4 v[188:191], v[188:189], off offset:192
	s_waitcnt lgkmcnt(2)
	v_mfma_f32_16x16x32_bf16 v[60:63], v[16:19], v[12:15], 0
	v_mfma_f32_16x16x32_bf16 v[16:19], v[16:19], v[44:47], 0
	s_waitcnt lgkmcnt(0)
	v_mfma_f32_16x16x32_bf16 v[60:63], v[172:175], v[40:43], v[60:63]
	v_mfma_f32_16x16x32_bf16 v[16:19], v[172:175], v[52:55], v[16:19]
	s_waitcnt vmcnt(3)
	v_mfma_f32_16x16x32_bf16 v[60:63], v[176:179], v[56:59], v[60:63]
	v_mfma_f32_16x16x32_bf16 v[16:19], v[176:179], v[80:83], v[16:19]
	ds_read_b64_tr_b16 v[172:173], v171 offset:224
	ds_read_b64_tr_b16 v[174:175], v171 offset:4576
	ds_read_b64_tr_b16 v[176:177], v171 offset:8928
	ds_read_b64_tr_b16 v[178:179], v171 offset:13280
	s_waitcnt vmcnt(2)
	v_mfma_f32_16x16x32_bf16 v[60:63], v[180:183], v[68:71], v[60:63]
	v_mfma_f32_16x16x32_bf16 v[16:19], v[180:183], v[84:87], v[16:19]
	s_waitcnt vmcnt(1)
	v_mfma_f32_16x16x32_bf16 v[60:63], v[184:187], v[72:75], v[60:63]
	v_mfma_f32_16x16x32_bf16 v[16:19], v[184:187], v[92:95], v[16:19]
	s_waitcnt vmcnt(0)
	v_mfma_f32_16x16x32_bf16 v[60:63], v[188:191], v[76:79], v[60:63]
	v_mfma_f32_16x16x32_bf16 v[16:19], v[188:191], v[96:99], v[16:19]
	global_load_dwordx4 v[180:183], v[132:133], off
	global_load_dwordx4 v[184:187], v[132:133], off offset:64
	global_load_dwordx4 v[188:191], v[132:133], off offset:128
	global_load_dwordx4 v[192:195], v[132:133], off offset:192
	s_load_dwordx2 s[4:5], s[0:1], 0x50
	s_waitcnt lgkmcnt(0)
	s_add_u32 s4, s4, s2
	v_mfma_f32_16x16x32_bf16 v[12:15], v[172:175], v[12:15], 0
	s_addc_u32 s5, s5, s3
	s_lshl_b32 s7, s34, 9
	s_add_u32 s4, s4, s7
	v_mfma_f32_16x16x32_bf16 v[12:15], v[176:179], v[40:43], v[12:15]
	s_addc_u32 s5, s5, 0
	s_ashr_i32 s7, s6, 31
	s_lshl_b64 s[8:9], s[6:7], 14
	s_waitcnt vmcnt(3)
	v_mfma_f32_16x16x32_bf16 v[12:15], v[180:183], v[56:59], v[12:15]
	s_add_u32 s8, s14, s8
	s_addc_u32 s9, s15, s9
	s_add_u32 s8, s8, s22
	s_waitcnt vmcnt(2)
	v_mfma_f32_16x16x32_bf16 v[12:15], v[184:187], v[68:71], v[12:15]
	s_addc_u32 s9, s9, 0
	v_lshlrev_b32_e32 v56, 1, v124
	v_mov_b32_e32 v57, v197
	s_waitcnt vmcnt(1)
	v_mfma_f32_16x16x32_bf16 v[12:15], v[188:191], v[72:75], v[12:15]
	s_lshl_b64 s[6:7], s[6:7], 10
	s_add_u32 s6, s24, s6
	s_addc_u32 s7, s25, s7
	s_waitcnt vmcnt(0)
; DI float sx(float v, int mask, int lane) { return __int_as_float(__builtin_amdgcn_ds_bpermute((lane ^ mask) << 2, __float_as_int(v))); }
; template <bool GROUPNORM>
; DI void wave_tail(f32x4 (&acc)[8][2], int lane, const float* gain, const bf16* gate0, bf16* out0, size_t gate_stride) {
;     ...
;         for (int et = 0; et < 8; ++et) gws[et] = *(const u32x2*)(gate0 + (size_t)(16 * x + lr) * gate_stride + 16 * et + 4 * g);
;         float s1 = 0.f, s2 = 0.f;
; #pragma unroll
;         for (int et = 0; et < 8; ++et)
; #pragma unroll
;             for (int r = 0; r < 4; ++r) { s1 += acc[et][x][r]; s2 += acc[et][x][r] * acc[et][x][r]; }
;         s1 += sx(s1, 16, lane); s1 += sx(s1, 32, lane); s2 += sx(s2, 16, lane); s2 += sx(s2, 32, lane);
;         const float mean = GROUPNORM ? s1 * (1.f / 128.f) : 0.f;
;         const float var = GROUPNORM ? fmaxf(s2 * (1.f / 128.f) - mean * mean, 0.f) : s2 * (1.f / 128.f);
;         const float rstd = rsqrtf(var + EPS);
;         bf16* op = out0 + (size_t)(16 * x + lr) * 512;
; #pragma unroll
;         for (int et = 0; et < 8; ++et) {
;             const int e0 = 16 * et + 4 * g;
;             const f32x4 gn = *(const f32x4*)(gain + e0);
	v_mfma_f32_16x16x32_bf16 v[40:43], v[192:195], v[76:79], v[12:15]
	s_add_u32 s6, s6, s22
	s_addc_u32 s7, s7, 0
	s_add_i32 s27, s27, s84
	v_mfma_f32_16x16x32_bf16 v[12:15], v[172:175], v[44:47], 0
	v_lshl_add_u64 v[44:45], s[8:9], 0, v[56:57]
	s_mov_b64 s[8:9], 0x2400
	s_cmpk_gt_i32 s27, 0x7ff
	v_mfma_f32_16x16x32_bf16 v[12:15], v[176:179], v[52:55], v[12:15]
	v_lshl_add_u64 v[54:55], v[44:45], 0, v[104:105]
	v_add_co_u32_e32 v46, vcc, s33, v54
	v_mfma_f32_16x16x32_bf16 v[12:15], v[180:183], v[80:83], v[12:15]
	v_lshl_add_u64 v[44:45], v[54:55], 0, s[8:9]
	v_addc_co_u32_e32 v47, vcc, 0, v55, vcc
	v_mfma_f32_16x16x32_bf16 v[12:15], v[184:187], v[84:87], v[12:15]
	global_load_dwordx2 v[86:87], v[46:47], off offset:1024
	global_load_dwordx2 v[84:85], v[44:45], off offset:32
	global_load_dwordx2 v[82:83], v[44:45], off offset:64
	global_load_dwordx2 v[80:81], v[44:45], off offset:96
	global_load_dwordx2 v[78:79], v[44:45], off offset:128
	global_load_dwordx2 v[76:77], v[44:45], off offset:160
	global_load_dwordx2 v[72:73], v[44:45], off offset:192
	global_load_dwordx2 v[68:69], v[44:45], off offset:224
	v_add_f32_e32 v44, 0, v36
	v_add_f32_e32 v44, v37, v44
	v_add_f32_e32 v44, v38, v44
	v_mul_f32_e32 v46, v37, v37
	v_add_f32_e32 v44, v39, v44
	v_fmac_f32_e32 v46, v36, v36
	v_add_f32_e32 v44, v44, v32
	v_fmac_f32_e32 v46, v38, v38
	v_add_f32_e32 v44, v33, v44
	v_fmac_f32_e32 v46, v39, v39
	v_add_f32_e32 v44, v34, v44
	v_fmac_f32_e32 v46, v32, v32
	v_add_f32_e32 v44, v35, v44
	v_fmac_f32_e32 v46, v33, v33
	v_add_f32_e32 v44, v44, v48
	v_fmac_f32_e32 v46, v34, v34
	v_add_f32_e32 v44, v49, v44
	v_fmac_f32_e32 v46, v35, v35
	v_add_f32_e32 v44, v50, v44
	v_fmac_f32_e32 v46, v48, v48
	v_add_f32_e32 v44, v51, v44
	v_fmac_f32_e32 v46, v49, v49
	v_add_f32_e32 v44, v44, v100
	v_fmac_f32_e32 v46, v50, v50
	v_add_f32_e32 v44, v101, v44
	v_fmac_f32_e32 v46, v51, v51
	v_add_f32_e32 v44, v102, v44
	v_fmac_f32_e32 v46, v100, v100
	v_add_f32_e32 v44, v103, v44
	v_fmac_f32_e32 v46, v101, v101
	v_add_f32_e32 v44, v44, v88
	v_fmac_f32_e32 v46, v102, v102
	v_add_f32_e32 v44, v89, v44
	v_fmac_f32_e32 v46, v103, v103
	v_add_f32_e32 v44, v90, v44
	v_fmac_f32_e32 v46, v88, v88
	v_add_f32_e32 v44, v91, v44
	v_fmac_f32_e32 v46, v89, v89
	v_add_f32_e32 v47, v44, v64
	v_pk_mov_b32 v[44:45], v[90:91], v[64:65] op_sel:[1,0]
	v_fmac_f32_e32 v46, v90, v90
	v_pk_mul_f32 v[44:45], v[44:45], v[44:45]
	v_lshlrev_b32_e32 v52, 2, v124
	v_add_f32_e32 v44, v44, v46
	v_add_f32_e32 v53, v44, v45
	v_add_f32_e32 v44, v65, v47
	v_add_f32_e32 v58, v66, v44
	v_pk_mul_f32 v[44:45], v[66:67], v[66:67]
	v_pk_mul_f32 v[46:47], v[64:65], v[64:65]
	v_mfma_f32_16x16x32_bf16 v[12:15], v[188:191], v[92:95], v[12:15]
	v_add_f32_e32 v45, v47, v53
	v_add_f32_e32 v46, v44, v45
	v_add_f32_e32 v44, v67, v58
	v_add_f32_e32 v47, v44, v60
	v_pk_mov_b32 v[44:45], v[66:67], v[60:61] op_sel:[1,0]
	v_mfma_f32_16x16x32_bf16 v[12:15], v[192:195], v[96:99], v[12:15]
	v_mul_f32_e64 v44, v44, v44
	v_mul_f32_e64 v45, v45, v45
	s_waitcnt vmcnt(7)
	v_lshlrev_b32_e32 v92, 16, v86
	v_add_f32_e32 v44, v44, v46
	v_add_f32_e32 v53, v44, v45
	v_add_f32_e32 v44, v61, v47
	v_add_f32_e32 v58, v62, v44
	v_pk_mul_f32 v[44:45], v[62:63], v[62:63]
	v_pk_mul_f32 v[46:47], v[60:61], v[60:61]
	v_and_b32_e32 v93, 0xffff0000, v86
	v_add_f32_e32 v45, v47, v53
	v_add_f32_e32 v46, v44, v45
	v_add_f32_e32 v44, v63, v58
	v_add_f32_e32 v47, v44, v40
	v_pk_mov_b32 v[44:45], v[62:63], v[40:41] op_sel:[1,0]
	v_pk_mul_f32 v[58:59], v[40:41], v[40:41]
	v_pk_mul_f32 v[44:45], v[44:45], v[44:45]
	v_mul_f32_e32 v53, 0xbfb8aa3b, v92
	v_add_f32_e32 v44, v44, v46
	v_add_f32_e32 v44, v44, v45
	v_add_f32_e32 v45, v41, v47
	v_pk_mul_f32 v[46:47], v[42:43], v[42:43]
	v_add_f32_e32 v44, v59, v44
	v_add_f32_e32 v45, v42, v45
	v_add_f32_e32 v46, v46, v44
	v_mul_f32_e32 v44, v43, v43
	v_mov_b32_e32 v47, v43
	v_pk_add_f32 v[44:45], v[46:47], v[44:45]
	ds_bpermute_b32 v47, v141, v45
	ds_bpermute_b32 v46, v141, v44
	v_exp_f32_e32 v53, v53
	v_lshl_add_u64 v[58:59], s[6:7], 0, v[106:107]
	s_waitcnt lgkmcnt(0)
	v_pk_add_f32 v[44:45], v[44:45], v[46:47]
	ds_bpermute_b32 v47, v142, v45
	ds_bpermute_b32 v46, v142, v44
	v_add_f32_e32 v53, 1.0, v53
	v_rcp_f32_e32 v94, v53
	s_waitcnt lgkmcnt(0)
	v_pk_add_f32 v[44:45], v[44:45], v[46:47]
	s_nop 0
	v_pk_mul_f32 v[70:71], v[44:45], s[18:19] op_sel_hi:[1,0]
	s_nop 0
	v_fma_f32 v44, -v71, v71, v70
	v_max_f32_e32 v44, 0, v44
	v_add_f32_e32 v44, 0x358637bd, v44
	v_cmp_gt_f32_e32 vcc, s67, v44
	v_mul_f32_e32 v45, 0x4b800000, v44
	v_pk_add_f32 v[36:37], v[36:37], v[70:71] op_sel:[0,1] neg_lo:[0,1] neg_hi:[0,1]
	v_cndmask_b32_e32 v44, v44, v45, vcc
	v_rsq_f32_e32 v44, v44
	v_pk_add_f32 v[38:39], v[38:39], v[70:71] op_sel:[0,1] neg_lo:[0,1] neg_hi:[0,1]
	v_pk_add_f32 v[32:33], v[32:33], v[70:71] op_sel:[0,1] neg_lo:[0,1] neg_hi:[0,1]
	v_pk_add_f32 v[34:35], v[34:35], v[70:71] op_sel:[0,1] neg_lo:[0,1] neg_hi:[0,1]
	v_mul_f32_e32 v45, 0x45800000, v44
	v_cndmask_b32_e32 v74, v44, v45, vcc
	global_load_dwordx4 v[200:203], v52, s[4:5]
	global_load_dwordx4 v[204:207], v52, s[4:5] offset:64
	global_load_dwordx4 v[208:211], v52, s[4:5] offset:128
	global_load_dwordx4 v[212:215], v52, s[4:5] offset:192
	global_load_dwordx4 v[216:219], v52, s[4:5] offset:256
	global_load_dwordx4 v[220:223], v52, s[4:5] offset:320
	global_load_dwordx4 v[232:235], v52, s[4:5] offset:384
	global_load_dwordx4 v[236:239], v52, s[4:5] offset:448
	v_pk_mul_f32 v[36:37], v[36:37], v[74:75] op_sel_hi:[1,0]
	v_pk_mul_f32 v[38:39], v[38:39], v[74:75] op_sel_hi:[1,0]
	v_pk_mul_f32 v[32:33], v[32:33], v[74:75] op_sel_hi:[1,0]
	v_pk_mul_f32 v[34:35], v[34:35], v[74:75] op_sel_hi:[1,0]
	v_pk_add_f32 v[40:41], v[40:41], v[70:71] op_sel:[0,1] neg_lo:[0,1] neg_hi:[0,1]
	v_pk_add_f32 v[42:43], v[42:43], v[70:71] op_sel:[0,1] neg_lo:[0,1] neg_hi:[0,1]
	v_pk_mul_f32 v[40:41], v[40:41], v[74:75] op_sel_hi:[1,0]
	v_pk_mul_f32 v[42:43], v[42:43], v[74:75] op_sel_hi:[1,0]
	s_waitcnt vmcnt(0)
; DI unsigned pk2(float lo, float hi) { f32x2_t v = {lo, hi}; bf16x2_t b = __builtin_convertvector(v, bf16x2_t); return __builtin_bit_cast(unsigned, b); }
; DI float bflo(unsigned w) { return __uint_as_float(w << 16); }
; DI float bfhi(unsigned w) { return __uint_as_float(w & 0xffff0000u); }
; DI float fsilu(float x) { return x * fsigmoid(x); }
; template <bool GROUPNORM>
; DI void wave_tail(f32x4 (&acc)[8][2], int lane, const float* gain, const bf16* gate0, bf16* out0, size_t gate_stride) {
;     ...
;         for (int et = 0; et < 8; ++et) {
;             const int e0 = 16 * et + 4 * g;
;             const f32x4 gn = *(const f32x4*)(gain + e0);
;             const u32x2 gw = gws[et];
;             const float y0 = (acc[et][x][0] - mean) * rstd * gn.x * fsilu(bflo(gw.x)), y1 = (acc[et][x][1] - mean) * rstd * gn.y * fsilu(bfhi(gw.x));
;             const float y2 = (acc[et][x][2] - mean) * rstd * gn.z * fsilu(bflo(gw.y)), y3 = (acc[et][x][3] - mean) * rstd * gn.w * fsilu(bfhi(gw.y));
;             u32x2 w; w.x = pk2(y0, y1); w.y = pk2(y2, y3);
;             *(u32x2*)(op + e0) = w;
;         }
	v_pk_mul_f32 v[36:37], v[200:201], v[36:37]
	v_mul_f32_e32 v44, 0xbfb8aa3b, v93
	v_exp_f32_e32 v44, v44
	v_pk_mul_f32 v[38:39], v[202:203], v[38:39]
	v_add_f32_e32 v44, 1.0, v44
	v_rcp_f32_e32 v95, v44
	s_nop 0
	v_pk_mul_f32 v[44:45], v[94:95], v[92:93]
	s_nop 0
	v_pk_mul_f32 v[36:37], v[44:45], v[36:37]
	v_lshlrev_b32_e32 v44, 16, v87
	v_and_b32_e32 v45, 0xffff0000, v87
	v_mul_f32_e32 v53, 0xbfb8aa3b, v44
	v_mul_f32_e32 v46, 0xbfb8aa3b, v45
	v_exp_f32_e32 v53, v53
	v_exp_f32_e32 v46, v46
	v_add_f32_e32 v53, 1.0, v53
	v_add_f32_e32 v46, 1.0, v46
	v_rcp_f32_e32 v86, v53
	v_rcp_f32_e32 v87, v46
	s_nop 0
	v_pk_mul_f32 v[44:45], v[86:87], v[44:45]
	s_nop 0
	v_pk_mul_f32 v[38:39], v[44:45], v[38:39]
	v_cvt_pk_bf16_f32 v44, v36, v37
	v_cvt_pk_bf16_f32 v45, v38, v39
	v_lshl_add_u64 v[36:37], v[58:59], 0, v[56:57]
	global_store_dwordx2 v[36:37], v[44:45], off
	v_lshlrev_b32_e32 v38, 16, v84
	v_and_b32_e32 v39, 0xffff0000, v84
	v_mul_f32_e32 v53, 0xbfb8aa3b, v38
	v_exp_f32_e32 v53, v53
	v_pk_mul_f32 v[32:33], v[204:205], v[32:33]
	v_mul_f32_e32 v44, 0xbfb8aa3b, v39
	v_exp_f32_e32 v44, v44
	v_add_f32_e32 v53, 1.0, v53
	v_rcp_f32_e32 v86, v53
	v_pk_mul_f32 v[34:35], v[206:207], v[34:35]
	v_add_f32_e32 v44, 1.0, v44
	v_rcp_f32_e32 v87, v44
	v_pk_add_f32 v[46:47], v[48:49], v[70:71] op_sel:[0,1] neg_lo:[0,1] neg_hi:[0,1]
	v_pk_mul_f32 v[38:39], v[86:87], v[38:39]
	s_nop 0
	v_pk_mul_f32 v[32:33], v[38:39], v[32:33]
	v_lshlrev_b32_e32 v38, 16, v85
	v_and_b32_e32 v39, 0xffff0000, v85
	v_mul_f32_e32 v44, 0xbfb8aa3b, v38
	v_mul_f32_e32 v45, 0xbfb8aa3b, v39
	v_exp_f32_e32 v44, v44
	v_exp_f32_e32 v45, v45
	v_cvt_pk_bf16_f32 v32, v32, v33
	v_pk_mul_f32 v[46:47], v[46:47], v[74:75] op_sel_hi:[1,0]
	v_add_f32_e32 v44, 1.0, v44
	v_add_f32_e32 v45, 1.0, v45
	v_rcp_f32_e32 v44, v44
	v_rcp_f32_e32 v45, v45
	s_nop 0
	v_pk_mul_f32 v[38:39], v[44:45], v[38:39]
	s_nop 0
	v_pk_mul_f32 v[34:35], v[38:39], v[34:35]
	v_lshlrev_b32_e32 v38, 16, v82
	v_cvt_pk_bf16_f32 v33, v34, v35
	global_store_dwordx2 v[36:37], v[32:33], off offset:32
	v_and_b32_e32 v39, 0xffff0000, v82
	v_mul_f32_e32 v44, 0xbfb8aa3b, v38
	v_mul_f32_e32 v45, 0xbfb8aa3b, v39
	v_exp_f32_e32 v44, v44
	v_exp_f32_e32 v45, v45
	v_add_f32_e32 v44, 1.0, v44
	v_add_f32_e32 v45, 1.0, v45
	v_rcp_f32_e32 v44, v44
	v_rcp_f32_e32 v45, v45
	v_pk_mul_f32 v[32:33], v[208:209], v[46:47]
	v_pk_mul_f32 v[38:39], v[44:45], v[38:39]
	v_pk_add_f32 v[46:47], v[50:51], v[70:71] op_sel:[0,1] neg_lo:[0,1] neg_hi:[0,1]
	v_pk_mul_f32 v[32:33], v[38:39], v[32:33]
	v_lshlrev_b32_e32 v38, 16, v83
	v_and_b32_e32 v39, 0xffff0000, v83
	v_mul_f32_e32 v44, 0xbfb8aa3b, v38
	v_mul_f32_e32 v45, 0xbfb8aa3b, v39
	v_exp_f32_e32 v44, v44
	v_exp_f32_e32 v45, v45
	v_pk_mul_f32 v[46:47], v[46:47], v[74:75] op_sel_hi:[1,0]
	v_cvt_pk_bf16_f32 v32, v32, v33
	v_add_f32_e32 v44, 1.0, v44
	v_add_f32_e32 v45, 1.0, v45
	v_rcp_f32_e32 v44, v44
	v_rcp_f32_e32 v45, v45
	v_pk_mul_f32 v[34:35], v[210:211], v[46:47]
	v_pk_add_f32 v[46:47], v[100:101], v[70:71] op_sel:[0,1] neg_lo:[0,1] neg_hi:[0,1]
	v_pk_mul_f32 v[38:39], v[44:45], v[38:39]
	s_nop 0
	v_pk_mul_f32 v[34:35], v[38:39], v[34:35]
	v_lshlrev_b32_e32 v38, 16, v80
	v_cvt_pk_bf16_f32 v33, v34, v35
	global_store_dwordx2 v[36:37], v[32:33], off offset:64
	v_and_b32_e32 v39, 0xffff0000, v80
	v_mul_f32_e32 v44, 0xbfb8aa3b, v38
	v_mul_f32_e32 v45, 0xbfb8aa3b, v39
	v_exp_f32_e32 v44, v44
	v_exp_f32_e32 v45, v45
	v_pk_mul_f32 v[46:47], v[46:47], v[74:75] op_sel_hi:[1,0]
	v_add_f32_e32 v44, 1.0, v44
	v_add_f32_e32 v45, 1.0, v45
	v_rcp_f32_e32 v44, v44
	v_rcp_f32_e32 v45, v45
	v_pk_mul_f32 v[32:33], v[212:213], v[46:47]
	v_pk_mul_f32 v[38:39], v[44:45], v[38:39]
	v_pk_add_f32 v[46:47], v[102:103], v[70:71] op_sel:[0,1] neg_lo:[0,1] neg_hi:[0,1]
	v_pk_mul_f32 v[32:33], v[38:39], v[32:33]
	v_lshlrev_b32_e32 v38, 16, v81
	v_and_b32_e32 v39, 0xffff0000, v81
	v_mul_f32_e32 v44, 0xbfb8aa3b, v38
	v_mul_f32_e32 v45, 0xbfb8aa3b, v39
	v_exp_f32_e32 v44, v44
	v_exp_f32_e32 v45, v45
	v_pk_mul_f32 v[46:47], v[46:47], v[74:75] op_sel_hi:[1,0]
	v_cvt_pk_bf16_f32 v32, v32, v33
	v_add_f32_e32 v44, 1.0, v44
	v_add_f32_e32 v45, 1.0, v45
	v_rcp_f32_e32 v44, v44
	v_rcp_f32_e32 v45, v45
	v_pk_mul_f32 v[34:35], v[214:215], v[46:47]
	v_pk_add_f32 v[46:47], v[88:89], v[70:71] op_sel:[0,1] neg_lo:[0,1] neg_hi:[0,1]
	v_pk_mul_f32 v[38:39], v[44:45], v[38:39]
	s_nop 0
	v_pk_mul_f32 v[34:35], v[38:39], v[34:35]
	v_lshlrev_b32_e32 v38, 16, v78
	v_cvt_pk_bf16_f32 v33, v34, v35
	global_store_dwordx2 v[36:37], v[32:33], off offset:96
	v_and_b32_e32 v39, 0xffff0000, v78
	v_mul_f32_e32 v44, 0xbfb8aa3b, v38
	v_mul_f32_e32 v45, 0xbfb8aa3b, v39
	v_exp_f32_e32 v44, v44
	v_exp_f32_e32 v45, v45
	v_pk_mul_f32 v[46:47], v[46:47], v[74:75] op_sel_hi:[1,0]
	v_add_f32_e32 v44, 1.0, v44
	v_add_f32_e32 v45, 1.0, v45
	v_rcp_f32_e32 v44, v44
	v_rcp_f32_e32 v45, v45
	v_pk_mul_f32 v[32:33], v[216:217], v[46:47]
	v_pk_mul_f32 v[38:39], v[44:45], v[38:39]
	v_pk_add_f32 v[46:47], v[90:91], v[70:71] op_sel:[0,1] neg_lo:[0,1] neg_hi:[0,1]
	v_pk_mul_f32 v[32:33], v[38:39], v[32:33]
	v_lshlrev_b32_e32 v38, 16, v79
	v_and_b32_e32 v39, 0xffff0000, v79
	v_mul_f32_e32 v44, 0xbfb8aa3b, v38
	v_mul_f32_e32 v45, 0xbfb8aa3b, v39
	v_exp_f32_e32 v44, v44
	v_exp_f32_e32 v45, v45
	v_pk_mul_f32 v[46:47], v[46:47], v[74:75] op_sel_hi:[1,0]
	v_cvt_pk_bf16_f32 v32, v32, v33
	v_add_f32_e32 v44, 1.0, v44
	v_add_f32_e32 v45, 1.0, v45
	v_rcp_f32_e32 v44, v44
	v_rcp_f32_e32 v45, v45
	v_pk_mul_f32 v[34:35], v[218:219], v[46:47]
	v_pk_add_f32 v[46:47], v[64:65], v[70:71] op_sel:[0,1] neg_lo:[0,1] neg_hi:[0,1]
	v_pk_mul_f32 v[38:39], v[44:45], v[38:39]
	s_nop 0
	v_pk_mul_f32 v[34:35], v[38:39], v[34:35]
; DI unsigned pk2(float lo, float hi) { f32x2_t v = {lo, hi}; bf16x2_t b = __builtin_convertvector(v, bf16x2_t); return __builtin_bit_cast(unsigned, b); }
; DI float bflo(unsigned w) { return __uint_as_float(w << 16); }
; DI float bfhi(unsigned w) { return __uint_as_float(w & 0xffff0000u); }
; DI float fsilu(float x) { return x * fsigmoid(x); }
; DI float sx(float v, int mask, int lane) { return __int_as_float(__builtin_amdgcn_ds_bpermute((lane ^ mask) << 2, __float_as_int(v))); }
; template <bool GROUPNORM>
; DI void wave_tail(f32x4 (&acc)[8][2], int lane, const float* gain, const bf16* gate0, bf16* out0, size_t gate_stride) {
;     ...
;     for (int x = 0; x < 2; ++x) {
;         u32x2 gws[8];
; #pragma unroll
;         for (int et = 0; et < 8; ++et) gws[et] = *(const u32x2*)(gate0 + (size_t)(16 * x + lr) * gate_stride + 16 * et + 4 * g);
;         float s1 = 0.f, s2 = 0.f;
; #pragma unroll
;         for (int et = 0; et < 8; ++et)
; #pragma unroll
;             for (int r = 0; r < 4; ++r) { s1 += acc[et][x][r]; s2 += acc[et][x][r] * acc[et][x][r]; }
;         s1 += sx(s1, 16, lane); s1 += sx(s1, 32, lane); s2 += sx(s2, 16, lane); s2 += sx(s2, 32, lane);
;     ...
;         for (int et = 0; et < 8; ++et) {
;             const int e0 = 16 * et + 4 * g;
;             const f32x4 gn = *(const f32x4*)(gain + e0);
;             const u32x2 gw = gws[et];
;             const float y0 = (acc[et][x][0] - mean) * rstd * gn.x * fsilu(bflo(gw.x)), y1 = (acc[et][x][1] - mean) * rstd * gn.y * fsilu(bfhi(gw.x));
;             const float y2 = (acc[et][x][2] - mean) * rstd * gn.z * fsilu(bflo(gw.y)), y3 = (acc[et][x][3] - mean) * rstd * gn.w * fsilu(bfhi(gw.y));
;             u32x2 w; w.x = pk2(y0, y1); w.y = pk2(y2, y3);
;             *(u32x2*)(op + e0) = w;
;         }
	v_lshlrev_b32_e32 v38, 16, v76
	v_cvt_pk_bf16_f32 v33, v34, v35
	global_store_dwordx2 v[36:37], v[32:33], off offset:128
	v_and_b32_e32 v39, 0xffff0000, v76
	v_mul_f32_e32 v44, 0xbfb8aa3b, v38
	v_mul_f32_e32 v45, 0xbfb8aa3b, v39
	v_exp_f32_e32 v44, v44
	v_exp_f32_e32 v45, v45
	v_pk_mul_f32 v[46:47], v[46:47], v[74:75] op_sel_hi:[1,0]
	v_add_f32_e32 v44, 1.0, v44
	v_add_f32_e32 v45, 1.0, v45
	v_rcp_f32_e32 v44, v44
	v_rcp_f32_e32 v45, v45
	v_pk_mul_f32 v[32:33], v[220:221], v[46:47]
	v_pk_mul_f32 v[38:39], v[44:45], v[38:39]
	v_pk_add_f32 v[46:47], v[66:67], v[70:71] op_sel:[0,1] neg_lo:[0,1] neg_hi:[0,1]
	v_pk_mul_f32 v[32:33], v[38:39], v[32:33]
	v_lshlrev_b32_e32 v38, 16, v77
	v_and_b32_e32 v39, 0xffff0000, v77
	v_mul_f32_e32 v44, 0xbfb8aa3b, v38
	v_mul_f32_e32 v45, 0xbfb8aa3b, v39
	v_exp_f32_e32 v44, v44
	v_exp_f32_e32 v45, v45
	v_pk_mul_f32 v[46:47], v[46:47], v[74:75] op_sel_hi:[1,0]
	v_cvt_pk_bf16_f32 v32, v32, v33
	v_add_f32_e32 v44, 1.0, v44
	v_add_f32_e32 v45, 1.0, v45
	v_rcp_f32_e32 v44, v44
	v_rcp_f32_e32 v45, v45
	v_pk_mul_f32 v[34:35], v[222:223], v[46:47]
	v_pk_add_f32 v[46:47], v[60:61], v[70:71] op_sel:[0,1] neg_lo:[0,1] neg_hi:[0,1]
	v_pk_mul_f32 v[38:39], v[44:45], v[38:39]
	s_nop 0
	v_pk_mul_f32 v[34:35], v[38:39], v[34:35]
	v_lshlrev_b32_e32 v38, 16, v72
	v_cvt_pk_bf16_f32 v33, v34, v35
	global_store_dwordx2 v[36:37], v[32:33], off offset:160
	v_and_b32_e32 v39, 0xffff0000, v72
	v_mul_f32_e32 v44, 0xbfb8aa3b, v38
	v_mul_f32_e32 v45, 0xbfb8aa3b, v39
	v_exp_f32_e32 v44, v44
	v_exp_f32_e32 v45, v45
	v_pk_mul_f32 v[46:47], v[46:47], v[74:75] op_sel_hi:[1,0]
	v_add_f32_e32 v44, 1.0, v44
	v_add_f32_e32 v45, 1.0, v45
	v_rcp_f32_e32 v44, v44
	v_rcp_f32_e32 v45, v45
	v_pk_mul_f32 v[32:33], v[46:47], v[232:233]
	v_pk_mul_f32 v[38:39], v[44:45], v[38:39]
	v_pk_add_f32 v[46:47], v[62:63], v[70:71] op_sel:[0,1] neg_lo:[0,1] neg_hi:[0,1]
	v_pk_mul_f32 v[32:33], v[38:39], v[32:33]
	v_lshlrev_b32_e32 v38, 16, v73
	v_and_b32_e32 v39, 0xffff0000, v73
	v_mul_f32_e32 v44, 0xbfb8aa3b, v38
	v_mul_f32_e32 v45, 0xbfb8aa3b, v39
	v_exp_f32_e32 v44, v44
	v_exp_f32_e32 v45, v45
	v_pk_mul_f32 v[46:47], v[46:47], v[74:75] op_sel_hi:[1,0]
	v_cvt_pk_bf16_f32 v32, v32, v33
	v_add_f32_e32 v44, 1.0, v44
	v_add_f32_e32 v45, 1.0, v45
	v_rcp_f32_e32 v44, v44
	v_rcp_f32_e32 v45, v45
	v_pk_mul_f32 v[34:35], v[46:47], v[234:235]
	v_pk_mul_f32 v[38:39], v[44:45], v[38:39]
	s_nop 0
	v_pk_mul_f32 v[34:35], v[38:39], v[34:35]
	v_lshlrev_b32_e32 v38, 16, v68
	v_cvt_pk_bf16_f32 v33, v34, v35
	global_store_dwordx2 v[36:37], v[32:33], off offset:192
	v_and_b32_e32 v39, 0xffff0000, v68
	v_mul_f32_e32 v44, 0xbfb8aa3b, v38
	v_exp_f32_e32 v44, v44
	v_pk_mul_f32 v[32:33], v[40:41], v[236:237]
	v_mul_f32_e32 v40, 0xbfb8aa3b, v39
	v_exp_f32_e32 v40, v40
	v_add_f32_e32 v44, 1.0, v44
	v_rcp_f32_e32 v44, v44
	v_pk_mul_f32 v[34:35], v[42:43], v[238:239]
	v_add_f32_e32 v40, 1.0, v40
	v_rcp_f32_e32 v45, v40
	s_nop 0
	v_pk_mul_f32 v[38:39], v[44:45], v[38:39]
	s_nop 0
	v_pk_mul_f32 v[32:33], v[38:39], v[32:33]
	v_lshlrev_b32_e32 v38, 16, v69
	v_and_b32_e32 v39, 0xffff0000, v69
	v_mul_f32_e32 v40, 0xbfb8aa3b, v38
	v_mul_f32_e32 v41, 0xbfb8aa3b, v39
	v_exp_f32_e32 v40, v40
	v_exp_f32_e32 v41, v41
	v_cvt_pk_bf16_f32 v32, v32, v33
	v_add_f32_e32 v40, 1.0, v40
	v_add_f32_e32 v41, 1.0, v41
	v_rcp_f32_e32 v40, v40
	v_rcp_f32_e32 v41, v41
	s_nop 0
	v_pk_mul_f32 v[38:39], v[40:41], v[38:39]
	s_nop 0
	v_pk_mul_f32 v[34:35], v[38:39], v[34:35]
	s_nop 0
	v_cvt_pk_bf16_f32 v33, v34, v35
	global_store_dwordx2 v[36:37], v[32:33], off offset:224
	v_add_co_u32_e32 v32, vcc, s40, v54
	v_mul_f32_e32 v34, v5, v5
	s_nop 0
	v_addc_co_u32_e32 v33, vcc, 0, v55, vcc
	global_load_dwordx2 v[62:63], v[32:33], off offset:1024
	global_load_dwordx2 v[60:61], v[32:33], off offset:1056
	global_load_dwordx2 v[54:55], v[32:33], off offset:1088
	global_load_dwordx2 v[50:51], v[32:33], off offset:1120
	global_load_dwordx2 v[48:49], v[32:33], off offset:1152
	global_load_dwordx2 v[46:47], v[32:33], off offset:1184
	global_load_dwordx2 v[44:45], v[32:33], off offset:1216
	global_load_dwordx2 v[38:39], v[32:33], off offset:1248
	v_add_f32_e32 v32, 0, v4
	v_add_f32_e32 v32, v5, v32
	v_add_f32_e32 v32, v6, v32
	v_add_f32_e32 v32, v7, v32
	v_fmac_f32_e32 v34, v4, v4
	v_add_f32_e32 v32, v32, v0
	v_fmac_f32_e32 v34, v6, v6
	v_add_f32_e32 v32, v1, v32
	v_fmac_f32_e32 v34, v7, v7
	v_add_f32_e32 v32, v2, v32
	v_fmac_f32_e32 v34, v0, v0
	v_add_f32_e32 v32, v3, v32
	v_fmac_f32_e32 v34, v1, v1
	v_add_f32_e32 v32, v32, v8
	v_fmac_f32_e32 v34, v2, v2
	v_add_f32_e32 v32, v9, v32
	v_fmac_f32_e32 v34, v3, v3
	v_add_f32_e32 v32, v10, v32
	v_fmac_f32_e32 v34, v8, v8
	v_add_f32_e32 v32, v11, v32
	v_fmac_f32_e32 v34, v9, v9
	v_add_f32_e32 v32, v32, v28
	v_fmac_f32_e32 v34, v10, v10
	v_add_f32_e32 v32, v29, v32
	v_fmac_f32_e32 v34, v11, v11
	v_add_f32_e32 v32, v30, v32
	v_fmac_f32_e32 v34, v28, v28
	v_add_f32_e32 v32, v31, v32
	v_fmac_f32_e32 v34, v29, v29
	v_add_f32_e32 v32, v32, v24
	v_fmac_f32_e32 v34, v30, v30
	v_add_f32_e32 v32, v25, v32
	v_fmac_f32_e32 v34, v31, v31
	v_add_f32_e32 v32, v26, v32
	v_fmac_f32_e32 v34, v24, v24
	v_add_f32_e32 v32, v27, v32
	v_fmac_f32_e32 v34, v25, v25
	v_add_f32_e32 v35, v32, v20
	v_pk_mov_b32 v[32:33], v[26:27], v[20:21] op_sel:[1,0]
	v_fmac_f32_e32 v34, v26, v26
	v_pk_mul_f32 v[32:33], v[32:33], v[32:33]
	s_nop 0
	v_add_f32_e32 v32, v32, v34
	v_add_f32_e32 v36, v32, v33
	v_add_f32_e32 v32, v21, v35
	v_add_f32_e32 v37, v22, v32
	v_pk_mul_f32 v[32:33], v[22:23], v[22:23]
	v_pk_mul_f32 v[34:35], v[20:21], v[20:21]
	s_nop 0
	v_add_f32_e32 v33, v35, v36
	v_add_f32_e32 v34, v32, v33
	v_add_f32_e32 v32, v23, v37
	v_add_f32_e32 v35, v32, v16
	v_pk_mov_b32 v[32:33], v[22:23], v[16:17] op_sel:[1,0]
	s_nop 0
	v_pk_mul_f32 v[32:33], v[32:33], v[32:33]
	s_nop 0
	v_add_f32_e32 v32, v32, v34
	v_add_f32_e32 v36, v32, v33
	v_add_f32_e32 v32, v17, v35
	v_add_f32_e32 v37, v18, v32
	v_pk_mul_f32 v[32:33], v[18:19], v[18:19]
	v_pk_mul_f32 v[34:35], v[16:17], v[16:17]
	s_nop 0
	v_add_f32_e32 v33, v35, v36
	v_add_f32_e32 v34, v32, v33
	v_add_f32_e32 v32, v19, v37
	v_add_f32_e32 v35, v32, v12
	v_pk_mov_b32 v[32:33], v[18:19], v[12:13] op_sel:[1,0]
	v_pk_mul_f32 v[36:37], v[12:13], v[12:13]
	v_pk_mul_f32 v[32:33], v[32:33], v[32:33]
	s_nop 0
	v_add_f32_e32 v32, v32, v34
	v_add_f32_e32 v32, v32, v33
	v_add_f32_e32 v33, v13, v35
	v_pk_mul_f32 v[34:35], v[14:15], v[14:15]
	v_add_f32_e32 v32, v37, v32
	v_add_f32_e32 v33, v14, v33
	v_add_f32_e32 v34, v34, v32
	v_mul_f32_e32 v32, v15, v15
	v_mov_b32_e32 v35, v15
	v_pk_add_f32 v[32:33], v[34:35], v[32:33]
	ds_bpermute_b32 v35, v141, v33
	ds_bpermute_b32 v34, v141, v32
	v_lshl_add_u64 v[36:37], v[58:59], 0, s[42:43]
	s_waitcnt vmcnt(7)
; DI unsigned pk2(float lo, float hi) { f32x2_t v = {lo, hi}; bf16x2_t b = __builtin_convertvector(v, bf16x2_t); return __builtin_bit_cast(unsigned, b); }
; DI float bflo(unsigned w) { return __uint_as_float(w << 16); }
; DI float bfhi(unsigned w) { return __uint_as_float(w & 0xffff0000u); }
; DI float fsilu(float x) { return x * fsigmoid(x); }
; template <bool GROUPNORM>
; DI void wave_tail(f32x4 (&acc)[8][2], int lane, const float* gain, const bf16* gate0, bf16* out0, size_t gate_stride) {
;     ...
;         const float mean = GROUPNORM ? s1 * (1.f / 128.f) : 0.f;
;         const float var = GROUPNORM ? fmaxf(s2 * (1.f / 128.f) - mean * mean, 0.f) : s2 * (1.f / 128.f);
;         const float rstd = rsqrtf(var + EPS);
;         bf16* op = out0 + (size_t)(16 * x + lr) * 512;
; #pragma unroll
;         for (int et = 0; et < 8; ++et) {
;             const int e0 = 16 * et + 4 * g;
;             const f32x4 gn = *(const f32x4*)(gain + e0);
;             const u32x2 gw = gws[et];
;             const float y0 = (acc[et][x][0] - mean) * rstd * gn.x * fsilu(bflo(gw.x)), y1 = (acc[et][x][1] - mean) * rstd * gn.y * fsilu(bfhi(gw.x));
;             const float y2 = (acc[et][x][2] - mean) * rstd * gn.z * fsilu(bflo(gw.y)), y3 = (acc[et][x][3] - mean) * rstd * gn.w * fsilu(bfhi(gw.y));
;             u32x2 w; w.x = pk2(y0, y1); w.y = pk2(y2, y3);
;             *(u32x2*)(op + e0) = w;
;         }
	v_lshlrev_b32_e32 v58, 16, v62
	v_mul_f32_e32 v43, 0xbfb8aa3b, v58
	v_exp_f32_e32 v43, v43
	s_waitcnt lgkmcnt(0)
	v_pk_add_f32 v[32:33], v[32:33], v[34:35]
	ds_bpermute_b32 v35, v142, v33
	ds_bpermute_b32 v34, v142, v32
	v_add_f32_e32 v43, 1.0, v43
	v_and_b32_e32 v59, 0xffff0000, v62
	v_rcp_f32_e32 v64, v43
	s_waitcnt lgkmcnt(0)
	v_pk_add_f32 v[32:33], v[32:33], v[34:35]
	s_nop 0
	v_pk_mul_f32 v[40:41], v[32:33], s[18:19] op_sel_hi:[1,0]
	s_nop 0
	v_fma_f32 v32, -v41, v41, v40
	v_max_f32_e32 v32, 0, v32
	v_add_f32_e32 v32, 0x358637bd, v32
	v_cmp_gt_f32_e32 vcc, s67, v32
	v_mul_f32_e32 v33, 0x4b800000, v32
	v_pk_add_f32 v[4:5], v[4:5], v[40:41] op_sel:[0,1] neg_lo:[0,1] neg_hi:[0,1]
	v_cndmask_b32_e32 v32, v32, v33, vcc
	v_rsq_f32_e32 v32, v32
	v_pk_add_f32 v[6:7], v[6:7], v[40:41] op_sel:[0,1] neg_lo:[0,1] neg_hi:[0,1]
	v_pk_add_f32 v[0:1], v[0:1], v[40:41] op_sel:[0,1] neg_lo:[0,1] neg_hi:[0,1]
	v_pk_add_f32 v[2:3], v[2:3], v[40:41] op_sel:[0,1] neg_lo:[0,1] neg_hi:[0,1]
	v_mul_f32_e32 v33, 0x45800000, v32
	v_cndmask_b32_e32 v42, v32, v33, vcc
	v_pk_mul_f32 v[4:5], v[4:5], v[42:43] op_sel_hi:[1,0]
	v_pk_add_f32 v[8:9], v[8:9], v[40:41] op_sel:[0,1] neg_lo:[0,1] neg_hi:[0,1]
	s_waitcnt vmcnt(0)
	v_pk_mul_f32 v[4:5], v[200:201], v[4:5]
	v_mul_f32_e32 v32, 0xbfb8aa3b, v59
	v_exp_f32_e32 v32, v32
	s_nop 0
	v_add_f32_e32 v32, 1.0, v32
	v_rcp_f32_e32 v65, v32
	s_nop 0
	v_pk_mul_f32 v[32:33], v[64:65], v[58:59]
	s_nop 0
	v_pk_mul_f32 v[4:5], v[32:33], v[4:5]
	v_lshlrev_b32_e32 v32, 16, v63
	v_mul_f32_e32 v43, 0xbfb8aa3b, v32
	v_exp_f32_e32 v43, v43
	v_and_b32_e32 v33, 0xffff0000, v63
	v_cvt_pk_bf16_f32 v4, v4, v5
	v_add_f32_e32 v43, 1.0, v43
	v_pk_mul_f32 v[6:7], v[6:7], v[42:43] op_sel_hi:[1,0]
	v_rcp_f32_e32 v58, v43
	v_pk_mul_f32 v[6:7], v[202:203], v[6:7]
	v_mul_f32_e32 v34, 0xbfb8aa3b, v33
	v_exp_f32_e32 v34, v34
	v_pk_mul_f32 v[0:1], v[0:1], v[42:43] op_sel_hi:[1,0]
	v_pk_mul_f32 v[2:3], v[2:3], v[42:43] op_sel_hi:[1,0]
	v_pk_mul_f32 v[8:9], v[8:9], v[42:43] op_sel_hi:[1,0]
	v_add_f32_e32 v34, 1.0, v34
	v_rcp_f32_e32 v59, v34
	s_nop 0
	v_pk_mul_f32 v[32:33], v[58:59], v[32:33]
	s_nop 0
	v_pk_mul_f32 v[6:7], v[32:33], v[6:7]
	v_lshlrev_b32_e32 v32, 16, v60
	v_cvt_pk_bf16_f32 v5, v6, v7
	v_lshl_add_u64 v[6:7], v[36:37], 0, v[56:57]
	global_store_dwordx2 v[6:7], v[4:5], off
	v_and_b32_e32 v33, 0xffff0000, v60
	v_mul_f32_e32 v34, 0xbfb8aa3b, v32
	v_exp_f32_e32 v34, v34
	v_pk_mul_f32 v[0:1], v[204:205], v[0:1]
	v_mul_f32_e32 v4, 0xbfb8aa3b, v33
	v_exp_f32_e32 v4, v4
	v_add_f32_e32 v34, 1.0, v34
	v_rcp_f32_e32 v34, v34
	v_pk_mul_f32 v[2:3], v[206:207], v[2:3]
	v_add_f32_e32 v4, 1.0, v4
	v_rcp_f32_e32 v35, v4
	s_nop 0
	v_pk_mul_f32 v[4:5], v[34:35], v[32:33]
	s_nop 0
	v_pk_mul_f32 v[0:1], v[4:5], v[0:1]
	v_lshlrev_b32_e32 v4, 16, v61
	v_and_b32_e32 v5, 0xffff0000, v61
	v_mul_f32_e32 v32, 0xbfb8aa3b, v4
	v_mul_f32_e32 v6, 0xbfb8aa3b, v5
	v_exp_f32_e32 v32, v32
	v_exp_f32_e32 v6, v6
	v_cvt_pk_bf16_f32 v0, v0, v1
	v_add_f32_e32 v32, 1.0, v32
	v_add_f32_e32 v6, 1.0, v6
	v_rcp_f32_e32 v32, v32
	v_rcp_f32_e32 v33, v6
	s_nop 0
	v_pk_mul_f32 v[4:5], v[32:33], v[4:5]
	s_nop 0
	v_pk_mul_f32 v[2:3], v[4:5], v[2:3]
	v_lshlrev_b32_e32 v4, 16, v54
	v_cvt_pk_bf16_f32 v1, v2, v3
	v_lshl_add_u64 v[2:3], v[36:37], 0, v[108:109]
	global_store_dwordx2 v[2:3], v[0:1], off
	v_and_b32_e32 v5, 0xffff0000, v54
	v_mul_f32_e32 v6, 0xbfb8aa3b, v4
	v_mul_f32_e32 v7, 0xbfb8aa3b, v5
	v_exp_f32_e32 v6, v6
	v_exp_f32_e32 v7, v7
	v_add_f32_e32 v6, 1.0, v6
	v_add_f32_e32 v7, 1.0, v7
	v_rcp_f32_e32 v6, v6
	v_rcp_f32_e32 v7, v7
	v_pk_mul_f32 v[0:1], v[208:209], v[8:9]
	v_pk_mul_f32 v[4:5], v[6:7], v[4:5]
	v_pk_add_f32 v[8:9], v[10:11], v[40:41] op_sel:[0,1] neg_lo:[0,1] neg_hi:[0,1]
	v_pk_mul_f32 v[0:1], v[4:5], v[0:1]
	v_lshlrev_b32_e32 v4, 16, v55
	v_and_b32_e32 v5, 0xffff0000, v55
	v_mul_f32_e32 v6, 0xbfb8aa3b, v4
	v_mul_f32_e32 v7, 0xbfb8aa3b, v5
	v_exp_f32_e32 v6, v6
	v_exp_f32_e32 v7, v7
	v_pk_mul_f32 v[8:9], v[8:9], v[42:43] op_sel_hi:[1,0]
	v_cvt_pk_bf16_f32 v0, v0, v1
	v_add_f32_e32 v6, 1.0, v6
	v_add_f32_e32 v7, 1.0, v7
	v_rcp_f32_e32 v6, v6
	v_rcp_f32_e32 v7, v7
	v_pk_mul_f32 v[2:3], v[210:211], v[8:9]
	v_pk_add_f32 v[8:9], v[28:29], v[40:41] op_sel:[0,1] neg_lo:[0,1] neg_hi:[0,1]
	v_pk_mul_f32 v[4:5], v[6:7], v[4:5]
	s_nop 0
	v_pk_mul_f32 v[2:3], v[4:5], v[2:3]
	v_lshlrev_b32_e32 v4, 16, v50
	v_cvt_pk_bf16_f32 v1, v2, v3
	v_lshl_add_u64 v[2:3], v[36:37], 0, v[110:111]
	global_store_dwordx2 v[2:3], v[0:1], off
	v_and_b32_e32 v5, 0xffff0000, v50
	v_mul_f32_e32 v6, 0xbfb8aa3b, v4
	v_mul_f32_e32 v7, 0xbfb8aa3b, v5
	v_exp_f32_e32 v6, v6
	v_exp_f32_e32 v7, v7
	v_pk_mul_f32 v[8:9], v[8:9], v[42:43] op_sel_hi:[1,0]
	v_add_f32_e32 v6, 1.0, v6
	v_add_f32_e32 v7, 1.0, v7
	v_rcp_f32_e32 v6, v6
	v_rcp_f32_e32 v7, v7
	v_pk_mul_f32 v[0:1], v[212:213], v[8:9]
	v_pk_mul_f32 v[4:5], v[6:7], v[4:5]
	v_pk_add_f32 v[8:9], v[30:31], v[40:41] op_sel:[0,1] neg_lo:[0,1] neg_hi:[0,1]
	v_pk_mul_f32 v[0:1], v[4:5], v[0:1]
	v_lshlrev_b32_e32 v4, 16, v51
	v_and_b32_e32 v5, 0xffff0000, v51
	v_mul_f32_e32 v6, 0xbfb8aa3b, v4
	v_mul_f32_e32 v7, 0xbfb8aa3b, v5
	v_exp_f32_e32 v6, v6
	v_exp_f32_e32 v7, v7
	v_pk_mul_f32 v[8:9], v[8:9], v[42:43] op_sel_hi:[1,0]
	v_cvt_pk_bf16_f32 v0, v0, v1
; DI unsigned pk2(float lo, float hi) { f32x2_t v = {lo, hi}; bf16x2_t b = __builtin_convertvector(v, bf16x2_t); return __builtin_bit_cast(unsigned, b); }
; DI float bflo(unsigned w) { return __uint_as_float(w << 16); }
; DI float bfhi(unsigned w) { return __uint_as_float(w & 0xffff0000u); }
; DI float fsilu(float x) { return x * fsigmoid(x); }
; template <bool GROUPNORM>
; DI void wave_tail(f32x4 (&acc)[8][2], int lane, const float* gain, const bf16* gate0, bf16* out0, size_t gate_stride) {
;     ...
;         for (int et = 0; et < 8; ++et) {
;             const int e0 = 16 * et + 4 * g;
;             const f32x4 gn = *(const f32x4*)(gain + e0);
;             const u32x2 gw = gws[et];
;             const float y0 = (acc[et][x][0] - mean) * rstd * gn.x * fsilu(bflo(gw.x)), y1 = (acc[et][x][1] - mean) * rstd * gn.y * fsilu(bfhi(gw.x));
;             const float y2 = (acc[et][x][2] - mean) * rstd * gn.z * fsilu(bflo(gw.y)), y3 = (acc[et][x][3] - mean) * rstd * gn.w * fsilu(bfhi(gw.y));
;             u32x2 w; w.x = pk2(y0, y1); w.y = pk2(y2, y3);
;             *(u32x2*)(op + e0) = w;
;         }
	v_add_f32_e32 v6, 1.0, v6
	v_add_f32_e32 v7, 1.0, v7
	v_rcp_f32_e32 v6, v6
	v_rcp_f32_e32 v7, v7
	v_pk_mul_f32 v[2:3], v[214:215], v[8:9]
	v_pk_add_f32 v[8:9], v[24:25], v[40:41] op_sel:[0,1] neg_lo:[0,1] neg_hi:[0,1]
	v_pk_mul_f32 v[4:5], v[6:7], v[4:5]
	s_nop 0
	v_pk_mul_f32 v[2:3], v[4:5], v[2:3]
	v_lshlrev_b32_e32 v4, 16, v48
	v_cvt_pk_bf16_f32 v1, v2, v3
	v_lshl_add_u64 v[2:3], v[36:37], 0, v[112:113]
	global_store_dwordx2 v[2:3], v[0:1], off
	v_and_b32_e32 v5, 0xffff0000, v48
	v_mul_f32_e32 v6, 0xbfb8aa3b, v4
	v_mul_f32_e32 v7, 0xbfb8aa3b, v5
	v_exp_f32_e32 v6, v6
	v_exp_f32_e32 v7, v7
	v_pk_mul_f32 v[8:9], v[8:9], v[42:43] op_sel_hi:[1,0]
	v_add_f32_e32 v6, 1.0, v6
	v_add_f32_e32 v7, 1.0, v7
	v_rcp_f32_e32 v6, v6
	v_rcp_f32_e32 v7, v7
	v_pk_mul_f32 v[0:1], v[216:217], v[8:9]
	v_pk_mul_f32 v[4:5], v[6:7], v[4:5]
	v_pk_add_f32 v[8:9], v[26:27], v[40:41] op_sel:[0,1] neg_lo:[0,1] neg_hi:[0,1]
	v_pk_mul_f32 v[0:1], v[4:5], v[0:1]
	v_lshlrev_b32_e32 v4, 16, v49
	v_and_b32_e32 v5, 0xffff0000, v49
	v_mul_f32_e32 v6, 0xbfb8aa3b, v4
	v_mul_f32_e32 v7, 0xbfb8aa3b, v5
	v_exp_f32_e32 v6, v6
	v_exp_f32_e32 v7, v7
	v_pk_mul_f32 v[8:9], v[8:9], v[42:43] op_sel_hi:[1,0]
	v_cvt_pk_bf16_f32 v0, v0, v1
	v_add_f32_e32 v6, 1.0, v6
	v_add_f32_e32 v7, 1.0, v7
	v_rcp_f32_e32 v6, v6
	v_rcp_f32_e32 v7, v7
	v_pk_mul_f32 v[2:3], v[218:219], v[8:9]
	v_pk_add_f32 v[8:9], v[20:21], v[40:41] op_sel:[0,1] neg_lo:[0,1] neg_hi:[0,1]
	v_pk_mul_f32 v[4:5], v[6:7], v[4:5]
	s_nop 0
	v_pk_mul_f32 v[2:3], v[4:5], v[2:3]
	v_lshlrev_b32_e32 v4, 16, v46
	v_cvt_pk_bf16_f32 v1, v2, v3
	v_lshl_add_u64 v[2:3], v[36:37], 0, v[114:115]
	global_store_dwordx2 v[2:3], v[0:1], off
	v_and_b32_e32 v5, 0xffff0000, v46
	v_mul_f32_e32 v6, 0xbfb8aa3b, v4
	v_mul_f32_e32 v7, 0xbfb8aa3b, v5
	v_exp_f32_e32 v6, v6
	v_exp_f32_e32 v7, v7
	v_pk_mul_f32 v[8:9], v[8:9], v[42:43] op_sel_hi:[1,0]
	v_add_f32_e32 v6, 1.0, v6
	v_add_f32_e32 v7, 1.0, v7
	v_rcp_f32_e32 v6, v6
	v_rcp_f32_e32 v7, v7
	v_pk_mul_f32 v[0:1], v[220:221], v[8:9]
	v_pk_mul_f32 v[4:5], v[6:7], v[4:5]
	v_pk_add_f32 v[8:9], v[22:23], v[40:41] op_sel:[0,1] neg_lo:[0,1] neg_hi:[0,1]
	v_pk_mul_f32 v[0:1], v[4:5], v[0:1]
	v_lshlrev_b32_e32 v4, 16, v47
	v_and_b32_e32 v5, 0xffff0000, v47
	v_mul_f32_e32 v6, 0xbfb8aa3b, v4
	v_mul_f32_e32 v7, 0xbfb8aa3b, v5
	v_exp_f32_e32 v6, v6
	v_exp_f32_e32 v7, v7
	v_pk_mul_f32 v[8:9], v[8:9], v[42:43] op_sel_hi:[1,0]
	v_cvt_pk_bf16_f32 v0, v0, v1
	v_add_f32_e32 v6, 1.0, v6
	v_add_f32_e32 v7, 1.0, v7
	v_rcp_f32_e32 v6, v6
	v_rcp_f32_e32 v7, v7
	v_pk_mul_f32 v[2:3], v[222:223], v[8:9]
	v_pk_add_f32 v[8:9], v[16:17], v[40:41] op_sel:[0,1] neg_lo:[0,1] neg_hi:[0,1]
	v_pk_mul_f32 v[4:5], v[6:7], v[4:5]
	s_nop 0
	v_pk_mul_f32 v[2:3], v[4:5], v[2:3]
	v_lshlrev_b32_e32 v4, 16, v44
	v_cvt_pk_bf16_f32 v1, v2, v3
	v_lshl_add_u64 v[2:3], v[36:37], 0, v[116:117]
	global_store_dwordx2 v[2:3], v[0:1], off
	v_and_b32_e32 v5, 0xffff0000, v44
	v_mul_f32_e32 v6, 0xbfb8aa3b, v4
	v_mul_f32_e32 v7, 0xbfb8aa3b, v5
	v_exp_f32_e32 v6, v6
	v_exp_f32_e32 v7, v7
	v_pk_mul_f32 v[8:9], v[8:9], v[42:43] op_sel_hi:[1,0]
	v_add_f32_e32 v6, 1.0, v6
	v_add_f32_e32 v7, 1.0, v7
	v_rcp_f32_e32 v6, v6
	v_rcp_f32_e32 v7, v7
	v_pk_mul_f32 v[0:1], v[8:9], v[232:233]
	v_pk_mul_f32 v[4:5], v[6:7], v[4:5]
	v_pk_add_f32 v[8:9], v[18:19], v[40:41] op_sel:[0,1] neg_lo:[0,1] neg_hi:[0,1]
	v_pk_mul_f32 v[0:1], v[4:5], v[0:1]
	v_lshlrev_b32_e32 v4, 16, v45
	v_and_b32_e32 v5, 0xffff0000, v45
	v_mul_f32_e32 v6, 0xbfb8aa3b, v4
	v_mul_f32_e32 v7, 0xbfb8aa3b, v5
	v_exp_f32_e32 v6, v6
	v_exp_f32_e32 v7, v7
	v_pk_mul_f32 v[8:9], v[8:9], v[42:43] op_sel_hi:[1,0]
	v_cvt_pk_bf16_f32 v0, v0, v1
	v_add_f32_e32 v6, 1.0, v6
	v_add_f32_e32 v7, 1.0, v7
	v_rcp_f32_e32 v6, v6
	v_rcp_f32_e32 v7, v7
	v_pk_mul_f32 v[2:3], v[8:9], v[234:235]
	v_pk_add_f32 v[8:9], v[12:13], v[40:41] op_sel:[0,1] neg_lo:[0,1] neg_hi:[0,1]
	v_pk_mul_f32 v[4:5], v[6:7], v[4:5]
	s_nop 0
	v_pk_mul_f32 v[2:3], v[4:5], v[2:3]
	v_lshlrev_b32_e32 v4, 16, v38
	v_cvt_pk_bf16_f32 v1, v2, v3
	v_lshl_add_u64 v[2:3], v[36:37], 0, v[118:119]
	global_store_dwordx2 v[2:3], v[0:1], off
	v_and_b32_e32 v5, 0xffff0000, v38
	v_mul_f32_e32 v6, 0xbfb8aa3b, v4
	v_mul_f32_e32 v7, 0xbfb8aa3b, v5
	v_exp_f32_e32 v6, v6
	v_exp_f32_e32 v7, v7
	v_pk_mul_f32 v[8:9], v[8:9], v[42:43] op_sel_hi:[1,0]
	v_add_f32_e32 v6, 1.0, v6
	v_add_f32_e32 v7, 1.0, v7
	v_rcp_f32_e32 v6, v6
	v_rcp_f32_e32 v7, v7
	v_pk_mul_f32 v[0:1], v[8:9], v[236:237]
	v_pk_mul_f32 v[4:5], v[6:7], v[4:5]
	v_pk_add_f32 v[8:9], v[14:15], v[40:41] op_sel:[0,1] neg_lo:[0,1] neg_hi:[0,1]
	v_pk_mul_f32 v[0:1], v[4:5], v[0:1]
	v_lshlrev_b32_e32 v4, 16, v39
	v_and_b32_e32 v5, 0xffff0000, v39
	v_mul_f32_e32 v6, 0xbfb8aa3b, v4
	v_mul_f32_e32 v7, 0xbfb8aa3b, v5
	v_exp_f32_e32 v6, v6
	v_exp_f32_e32 v7, v7
	v_pk_mul_f32 v[8:9], v[8:9], v[42:43] op_sel_hi:[1,0]
	v_cvt_pk_bf16_f32 v0, v0, v1
	v_add_f32_e32 v6, 1.0, v6
	v_add_f32_e32 v7, 1.0, v7
	v_rcp_f32_e32 v6, v6
	v_rcp_f32_e32 v7, v7
	v_pk_mul_f32 v[2:3], v[8:9], v[238:239]
	v_pk_mul_f32 v[4:5], v[6:7], v[4:5]
	s_nop 0
	v_pk_mul_f32 v[2:3], v[4:5], v[2:3]
	s_nop 0
	v_cvt_pk_bf16_f32 v1, v2, v3
	v_lshl_add_u64 v[2:3], v[36:37], 0, v[120:121]
	global_store_dwordx2 v[2:3], v[0:1], off
	s_waitcnt lgkmcnt(0)
	s_cbranch_scc1 .LBB0_506

; #define MFMA16(a, b, c) __builtin_amdgcn_mfma_f32_16x16x32_bf16((a), (b), (c), 0, 0, 0)
; DI void wave_gla_out(CP p, int l, int u, int ih, int lane) {
;     const int g = lane >> 4, lr = lane & 15;
;     const bf16* proj = (const bf16*)(p->ws + WS_PROJ);
;     const int bh = u >> 5, n = u & 31, b = bh >> 2, h = bh & 3, tok0 = b * SEQ + n * 64;
;     bf16x8 qf[2][2];
; #pragma unroll
;     for (int x = 0; x < 2; ++x)
; #pragma unroll
;         for (int ks = 0; ks < 2; ++ks) qf[x][ks] = *(const bf16x8*)(proj + (size_t)(tok0 + 32 * ih + 16 * x + lr) * NPROJ + C_GQ + h * 64 + ks * 32 + g * 8);
;     const bf16* st = (const bf16*)(p->ws + WS_GST) + (size_t)u * 8192;
;     f32x4 acc[8][2];
;     bf16x8 sa[8][2];
; #pragma unroll
;     for (int et = 0; et < 8; ++et)
; #pragma unroll
;         for (int ks = 0; ks < 2; ++ks) sa[et][ks] = *(const bf16x8*)(st + (size_t)(16 * et + lr) * 64 + ks * 32 + g * 8);
; #pragma unroll
;     for (int et = 0; et < 8; ++et)
; #pragma unroll
;         for (int x = 0; x < 2; ++x) { f32x4 a = {0.f, 0.f, 0.f, 0.f};
; #pragma unroll
;             for (int ks = 0; ks < 2; ++ks) a = MFMA16(sa[et][ks], qf[x][ks], a);
;             acc[et][x] = a * 0.125f; }
.LBB0_507:
	s_ashr_i32 s4, s12, 1
	s_lshl_b32 s3, s4, 6
	s_lshl_b32 s2, s4, 4
	s_and_b32 s3, s3, 0x7c0
	s_and_b32 s5, s8, 32
	s_and_b32 s2, s2, 0xfffff800
	s_or_b32 s3, s3, s5
	s_or_b32 s2, s3, s2
	v_or_b32_e32 v8, s2, v140
	v_ashrrev_i32_e32 v9, 31, v8
	s_bfe_u32 s9, s4, 0x20005
	v_lshlrev_b64 v[0:1], 14, v[8:9]
	v_or_b32_e32 v8, 16, v8
	v_lshl_add_u64 v[0:1], s[0:1], 0, v[0:1]
	s_lshl_b32 s22, s9, 7
	v_ashrrev_i32_e32 v9, 31, v8
	v_lshl_add_u64 v[0:1], v[0:1], 0, s[22:23]
	v_lshlrev_b64 v[8:9], 14, v[8:9]
	v_lshl_add_u64 v[0:1], v[0:1], 0, v[196:197]
	v_lshl_add_u64 v[8:9], s[0:1], 0, v[8:9]
	v_lshl_add_u64 v[4:5], v[0:1], 0, s[24:25]
	v_add_co_u32_e32 v0, vcc, s33, v0
	v_lshl_add_u64 v[8:9], v[8:9], 0, s[22:23]
	s_nop 0
	v_addc_co_u32_e32 v1, vcc, 0, v1, vcc
	v_lshl_add_u64 v[8:9], v[8:9], 0, v[196:197]
	v_lshl_add_u64 v[12:13], v[8:9], 0, s[24:25]
	v_add_co_u32_e32 v8, vcc, s33, v8
	s_ashr_i32 s5, s4, 31
	s_nop 0
	v_addc_co_u32_e32 v9, vcc, 0, v9, vcc
	global_load_dwordx4 v[0:3], v[0:1], off offset:2048
	s_nop 0
	global_load_dwordx4 v[4:7], v[4:5], off offset:64
	s_nop 0
	global_load_dwordx4 v[8:11], v[8:9], off offset:2048
	s_nop 0
	global_load_dwordx4 v[12:15], v[12:13], off offset:64
	s_lshl_b64 s[4:5], s[4:5], 14
	v_lshl_add_u64 v[16:17], v[58:59], 0, s[4:5]
	global_load_dwordx4 v[62:65], v[16:17], off
	global_load_dwordx4 v[66:69], v[16:17], off offset:64
	global_load_dwordx4 v[74:77], v[16:17], off offset:2048
	global_load_dwordx4 v[78:81], v[16:17], off offset:2112
	v_add_co_u32_e32 v18, vcc, s13, v16
	s_ashr_i32 s3, s2, 31
	s_nop 0
	v_addc_co_u32_e32 v19, vcc, 0, v17, vcc
	v_add_co_u32_e32 v20, vcc, s33, v16
	s_lshl_b64 s[4:5], s[2:3], 14
	s_nop 0
	v_addc_co_u32_e32 v21, vcc, 0, v17, vcc
	global_load_dwordx4 v[90:93], v[20:21], off offset:-4096
	global_load_dwordx4 v[94:97], v[18:19], off offset:64
	global_load_dwordx4 v[48:51], v[18:19], off offset:2048
	global_load_dwordx4 v[52:55], v[18:19], off offset:2112
	global_load_dwordx4 v[40:43], v[20:21], off
	global_load_dwordx4 v[44:47], v[20:21], off offset:64
	global_load_dwordx4 v[32:35], v[20:21], off offset:2048
	global_load_dwordx4 v[36:39], v[20:21], off offset:2112
	v_add_co_u32_e32 v20, vcc, s77, v16
	s_add_u32 s4, s0, s4
	s_nop 0
	v_addc_co_u32_e32 v21, vcc, 0, v17, vcc
	global_load_dwordx4 v[24:27], v[20:21], off
	global_load_dwordx4 v[28:31], v[20:21], off offset:64
	global_load_dwordx4 v[16:19], v[20:21], off offset:2048
	s_nop 0
	global_load_dwordx4 v[20:23], v[20:21], off offset:2112
	s_addc_u32 s5, s1, s5
	s_lshl_b32 s9, s9, 8
	s_add_u32 s4, s4, s9
	s_addc_u32 s5, s5, 0
	v_mov_b32_e32 v57, v197
	v_mov_b32_e32 v105, v197
	s_lshl_b64 s[2:3], s[2:3], 10
	s_add_u32 s2, s6, s2
	s_addc_u32 s3, s7, s3
	s_add_u32 s2, s2, s9
	s_addc_u32 s3, s3, 0
	v_mov_b32_e32 v107, v197
	v_mov_b32_e32 v109, v197
	v_mov_b32_e32 v111, v197
	v_mov_b32_e32 v113, v197
	v_mov_b32_e32 v115, v197
	v_mov_b32_e32 v117, v197
	v_mov_b32_e32 v119, v197
	v_mov_b32_e32 v121, v197
	s_add_i32 s12, s12, s84
	s_add_i32 s8, s8, s55
	s_cmpk_gt_i32 s12, 0x7ff
	s_waitcnt vmcnt(15)
	v_mfma_f32_16x16x32_bf16 v[70:73], v[62:65], v[0:3], 0
	v_mfma_f32_16x16x32_bf16 v[62:65], v[62:65], v[8:11], 0
	s_waitcnt vmcnt(14)
	v_mfma_f32_16x16x32_bf16 v[70:73], v[66:69], v[4:7], v[70:73]
	v_mfma_f32_16x16x32_bf16 v[62:65], v[66:69], v[12:15], v[62:65]
	s_nop 6
	v_mul_f32_e64 v86, v72, s16
	v_mul_f32_e64 v87, v73, s16
	v_pk_mul_f32 v[88:89], v[70:71], s[16:17] op_sel_hi:[1,0]
	v_pk_mul_f32 v[70:71], v[64:65], s[16:17] op_sel_hi:[1,0]
	v_pk_mul_f32 v[72:73], v[62:63], s[16:17] op_sel_hi:[1,0]
	s_waitcnt vmcnt(13)
	v_mfma_f32_16x16x32_bf16 v[62:65], v[74:77], v[0:3], 0
	v_mov_b32_e32 v144, v73
	v_mov_b32_e32 v145, v89
	v_pk_mul_f32 v[144:145], v[144:145], v[144:145]
	s_waitcnt vmcnt(12)
	v_mfma_f32_16x16x32_bf16 v[62:65], v[78:81], v[4:7], v[62:65]
	s_nop 7
	v_pk_mul_f32 v[82:83], v[64:65], s[16:17] op_sel_hi:[1,0]
	v_pk_mul_f32 v[84:85], v[62:63], s[16:17] op_sel_hi:[1,0]
	v_mfma_f32_16x16x32_bf16 v[62:65], v[74:77], v[8:11], 0
	v_mfma_f32_16x16x32_bf16 v[62:65], v[78:81], v[12:15], v[62:65]
	s_nop 7
	v_pk_mul_f32 v[66:67], v[64:65], s[16:17] op_sel_hi:[1,0]
	v_pk_mul_f32 v[68:69], v[62:63], s[16:17] op_sel_hi:[1,0]
	s_waitcnt vmcnt(11)
	v_mfma_f32_16x16x32_bf16 v[62:65], v[90:93], v[0:3], 0
	s_waitcnt vmcnt(10)
	v_mfma_f32_16x16x32_bf16 v[62:65], v[94:97], v[4:7], v[62:65]
	s_nop 7
	v_pk_mul_f32 v[78:79], v[64:65], s[16:17] op_sel_hi:[1,0]
	v_pk_mul_f32 v[80:81], v[62:63], s[16:17] op_sel_hi:[1,0]
	v_mfma_f32_16x16x32_bf16 v[62:65], v[90:93], v[8:11], 0
	v_mfma_f32_16x16x32_bf16 v[74:77], v[94:97], v[12:15], v[62:65]
	s_nop 7
	v_pk_mul_f32 v[62:63], v[76:77], s[16:17] op_sel_hi:[1,0]
	v_pk_mul_f32 v[64:65], v[74:75], s[16:17] op_sel_hi:[1,0]
	s_waitcnt vmcnt(9)
	v_mfma_f32_16x16x32_bf16 v[74:77], v[48:51], v[0:3], 0
	v_mfma_f32_16x16x32_bf16 v[48:51], v[48:51], v[8:11], 0
	s_waitcnt vmcnt(8)
	v_mfma_f32_16x16x32_bf16 v[90:93], v[52:55], v[4:7], v[74:77]
	v_mfma_f32_16x16x32_bf16 v[50:53], v[52:55], v[12:15], v[48:51]
	s_nop 6
	v_mul_f32_e64 v74, v92, s16
	v_mul_f32_e64 v75, v93, s16
	v_pk_mul_f32 v[48:49], v[52:53], s[16:17] op_sel_hi:[1,0]
	s_waitcnt vmcnt(7)
	v_mfma_f32_16x16x32_bf16 v[52:55], v[40:43], v[0:3], 0
	v_mul_f32_e64 v76, v90, s16
	v_mul_f32_e64 v77, v91, s16
	v_pk_mul_f32 v[50:51], v[50:51], s[16:17] op_sel_hi:[1,0]
	v_mov_b32_e32 v146, v48
	v_mfma_f32_16x16x32_bf16 v[40:43], v[40:43], v[8:11], 0
	v_mov_b32_e32 v147, v74
	s_waitcnt vmcnt(6)
	v_mfma_f32_16x16x32_bf16 v[90:93], v[44:47], v[4:7], v[52:55]
	v_mfma_f32_16x16x32_bf16 v[42:45], v[44:47], v[12:15], v[40:43]
	s_nop 6
	v_mul_f32_e64 v52, v92, s16
	v_mul_f32_e64 v53, v93, s16
	v_pk_mul_f32 v[40:41], v[44:45], s[16:17] op_sel_hi:[1,0]
	s_waitcnt vmcnt(5)
; DI float bflo(unsigned w) { return __uint_as_float(w << 16); }
; DI float bfhi(unsigned w) { return __uint_as_float(w & 0xffff0000u); }
; DI float fsilu(float x) { return x * fsigmoid(x); }
; #define MFMA16(a, b, c) __builtin_amdgcn_mfma_f32_16x16x32_bf16((a), (b), (c), 0, 0, 0)
; template <bool GROUPNORM>
; DI void wave_tail(f32x4 (&acc)[8][2], int lane, const float* gain, const bf16* gate0, bf16* out0, size_t gate_stride) {
;     ...
;         u32x2 gws[8];
; #pragma unroll
;         for (int et = 0; et < 8; ++et) gws[et] = *(const u32x2*)(gate0 + (size_t)(16 * x + lr) * gate_stride + 16 * et + 4 * g);
;     ...
;             const float y0 = (acc[et][x][0] - mean) * rstd * gn.x * fsilu(bflo(gw.x)), y1 = (acc[et][x][1] - mean) * rstd * gn.y * fsilu(bfhi(gw.x));
;             const float y2 = (acc[et][x][2] - mean) * rstd * gn.z * fsilu(bflo(gw.y)), y3 = (acc[et][x][3] - mean) * rstd * gn.w * fsilu(bfhi(gw.y));
; DI void wave_gla_out(CP p, int l, int u, int ih, int lane) {
;     ...
;     for (int et = 0; et < 8; ++et)
; #pragma unroll
;         for (int x = 0; x < 2; ++x) { f32x4 a = {0.f, 0.f, 0.f, 0.f};
; #pragma unroll
;             for (int ks = 0; ks < 2; ++ks) a = MFMA16(sa[et][ks], qf[x][ks], a);
;             acc[et][x] = a * 0.125f; }
	v_mfma_f32_16x16x32_bf16 v[44:47], v[32:35], v[0:3], 0
	v_mul_f32_e64 v54, v90, s16
	v_mul_f32_e64 v55, v91, s16
	v_pk_mul_f32 v[42:43], v[42:43], s[16:17] op_sel_hi:[1,0]
	v_mfma_f32_16x16x32_bf16 v[32:35], v[32:35], v[8:11], 0
	s_waitcnt vmcnt(4)
	v_mfma_f32_16x16x32_bf16 v[90:93], v[36:39], v[4:7], v[44:47]
	v_mfma_f32_16x16x32_bf16 v[34:37], v[36:39], v[12:15], v[32:35]
	s_nop 6
	v_mul_f32_e64 v44, v92, s16
	v_mul_f32_e64 v45, v93, s16
	v_pk_mul_f32 v[32:33], v[36:37], s[16:17] op_sel_hi:[1,0]
	s_waitcnt vmcnt(3)
	v_mfma_f32_16x16x32_bf16 v[36:39], v[24:27], v[0:3], 0
	v_mul_f32_e64 v46, v90, s16
	v_mul_f32_e64 v47, v91, s16
	v_pk_mul_f32 v[34:35], v[34:35], s[16:17] op_sel_hi:[1,0]
	v_mfma_f32_16x16x32_bf16 v[24:27], v[24:27], v[8:11], 0
	s_waitcnt vmcnt(1)
	v_mfma_f32_16x16x32_bf16 v[0:3], v[16:19], v[0:3], 0
	v_mfma_f32_16x16x32_bf16 v[90:93], v[28:31], v[4:7], v[36:39]
	v_mfma_f32_16x16x32_bf16 v[26:29], v[28:31], v[12:15], v[24:27]
	s_waitcnt vmcnt(0)
	v_mfma_f32_16x16x32_bf16 v[0:3], v[20:23], v[4:7], v[0:3]
	s_nop 4
	v_mul_f32_e64 v36, v92, s16
	v_mul_f32_e64 v37, v93, s16
	v_pk_mul_f32 v[24:25], v[28:29], s[16:17] op_sel_hi:[1,0]
	v_pk_mul_f32 v[38:39], v[90:91], s[16:17] op_sel_hi:[1,0]
	v_pk_mul_f32 v[26:27], v[26:27], s[16:17] op_sel_hi:[1,0]
	v_pk_mul_f32 v[136:137], v[38:39], v[38:39]
	v_pk_mul_f32 v[28:29], v[2:3], s[16:17] op_sel_hi:[1,0]
	v_pk_mul_f32 v[30:31], v[0:1], s[16:17] op_sel_hi:[1,0]
	v_mfma_f32_16x16x32_bf16 v[0:3], v[16:19], v[8:11], 0
	v_mul_f32_e64 v148, v26, v26
	v_mul_f32_e64 v149, v27, v27
	v_pk_mul_f32 v[130:131], v[36:37], v[36:37]
	v_pk_mul_f32 v[128:129], v[30:31], v[30:31]
	v_mfma_f32_16x16x32_bf16 v[0:3], v[20:23], v[12:15], v[0:3]
	v_mul_f32_e64 v96, v28, v28
	v_mul_f32_e64 v97, v29, v29
	v_lshl_add_u64 v[10:11], s[2:3], 0, v[106:107]
	s_mov_b32 s2, 0x43000
	s_nop 3
	v_pk_mul_f32 v[6:7], v[0:1], s[16:17] op_sel_hi:[1,0]
	v_lshl_add_u64 v[0:1], s[4:5], 0, v[56:57]
	v_lshl_add_u64 v[8:9], v[0:1], 0, v[104:105]
	v_pk_mul_f32 v[4:5], v[2:3], s[16:17] op_sel_hi:[1,0]
	v_add_co_u32_e32 v2, vcc, s77, v8
	v_lshl_add_u64 v[0:1], v[8:9], 0, s[26:27]
	s_nop 0
	v_addc_co_u32_e32 v3, vcc, 0, v9, vcc
	global_load_dwordx2 v[12:13], v[2:3], off
	global_load_dwordx2 v[92:93], v[0:1], off offset:32
	global_load_dwordx2 v[90:91], v[0:1], off offset:64
	global_load_dwordx2 v[22:23], v[0:1], off offset:96
	global_load_dwordx2 v[18:19], v[0:1], off offset:128
	global_load_dwordx2 v[14:15], v[0:1], off offset:160
	global_load_dwordx2 v[16:17], v[0:1], off offset:192
	global_load_dwordx2 v[20:21], v[0:1], off offset:224
	v_pk_mul_f32 v[150:151], v[6:7], v[6:7]
	global_load_dwordx4 v[200:203], v[60:61], off
	global_load_dwordx4 v[204:207], v[60:61], off offset:64
	global_load_dwordx4 v[208:211], v[60:61], off offset:128
	global_load_dwordx4 v[212:215], v[60:61], off offset:192
	global_load_dwordx4 v[216:219], v[60:61], off offset:256
	global_load_dwordx4 v[220:223], v[60:61], off offset:320
	global_load_dwordx4 v[232:235], v[60:61], off offset:384
	global_load_dwordx4 v[236:239], v[60:61], off offset:448
	s_waitcnt vmcnt(15)
	v_lshlrev_b32_e32 v94, 16, v12
	v_and_b32_e32 v95, 0xffff0000, v12
	v_mul_f32_e32 v12, 0xbfb8aa3b, v94
	v_exp_f32_e32 v12, v12
	s_nop 0
	v_add_f32_e32 v12, 1.0, v12
	v_rcp_f32_e32 v98, v12
	v_mul_f32_e32 v12, 0xbfb8aa3b, v95
	v_exp_f32_e32 v12, v12
	s_nop 0
	v_add_f32_e32 v12, 1.0, v12
	v_rcp_f32_e32 v99, v12
	v_lshlrev_b32_e32 v12, 16, v13
	v_and_b32_e32 v13, 0xffff0000, v13
	v_pk_mul_f32 v[122:123], v[98:99], v[94:95]
	v_mul_f32_e32 v94, 0xbfb8aa3b, v12
	v_mul_f32_e32 v95, 0xbfb8aa3b, v13
	v_exp_f32_e32 v94, v94
	v_exp_f32_e32 v95, v95
	v_add_f32_e32 v94, 1.0, v94
	v_add_f32_e32 v95, 1.0, v95
	v_rcp_f32_e32 v94, v94
	v_rcp_f32_e32 v95, v95
	s_nop 0
	v_pk_mul_f32 v[102:103], v[94:95], v[12:13]
	s_waitcnt vmcnt(14)
	v_lshlrev_b32_e32 v94, 16, v92
	v_and_b32_e32 v95, 0xffff0000, v92
	v_mul_f32_e32 v92, 0xbfb8aa3b, v94
	v_exp_f32_e32 v92, v92
	v_lshl_add_u64 v[12:13], v[10:11], 0, v[56:57]
	v_add_f32_e32 v92, 1.0, v92
	v_rcp_f32_e32 v98, v92
	v_mul_f32_e32 v92, 0xbfb8aa3b, v95
	v_exp_f32_e32 v92, v92
	s_nop 0
	v_add_f32_e32 v92, 1.0, v92
	v_rcp_f32_e32 v99, v92
	v_lshlrev_b32_e32 v92, 16, v93
	v_and_b32_e32 v93, 0xffff0000, v93
	v_pk_mul_f32 v[134:135], v[98:99], v[94:95]
	v_mul_f32_e32 v94, 0xbfb8aa3b, v92
	v_mul_f32_e32 v95, 0xbfb8aa3b, v93
	v_exp_f32_e32 v94, v94
	v_exp_f32_e32 v95, v95
	v_add_f32_e32 v94, 1.0, v94
	v_add_f32_e32 v95, 1.0, v95
	v_rcp_f32_e32 v94, v94
	v_rcp_f32_e32 v95, v95
	s_nop 0
	v_pk_mul_f32 v[132:133], v[94:95], v[92:93]
	s_waitcnt vmcnt(13)
	v_lshlrev_b32_e32 v92, 16, v90
	v_and_b32_e32 v93, 0xffff0000, v90
	v_mul_f32_e32 v90, 0xbfb8aa3b, v92
	v_exp_f32_e32 v90, v90
	s_nop 0
	v_add_f32_e32 v90, 1.0, v90
	v_rcp_f32_e32 v94, v90
	v_mul_f32_e32 v90, 0xbfb8aa3b, v93
	v_exp_f32_e32 v90, v90
	s_nop 0
	v_add_f32_e32 v90, 1.0, v90
	v_rcp_f32_e32 v95, v90
	v_lshlrev_b32_e32 v90, 16, v91
	v_and_b32_e32 v91, 0xffff0000, v91
	v_pk_mul_f32 v[126:127], v[94:95], v[92:93]
	v_mul_f32_e32 v92, 0xbfb8aa3b, v90
	v_mul_f32_e32 v93, 0xbfb8aa3b, v91
	v_exp_f32_e32 v92, v92
	v_exp_f32_e32 v93, v93
	v_add_f32_e32 v92, 1.0, v92
	v_add_f32_e32 v93, 1.0, v93
	v_rcp_f32_e32 v92, v92
	v_rcp_f32_e32 v93, v93
	s_nop 0
	v_pk_mul_f32 v[124:125], v[92:93], v[90:91]
	s_waitcnt vmcnt(12)
; DI float bflo(unsigned w) { return __uint_as_float(w << 16); }
; DI float bfhi(unsigned w) { return __uint_as_float(w & 0xffff0000u); }
; DI float fsilu(float x) { return x * fsigmoid(x); }
; DI float sx(float v, int mask, int lane) { return __int_as_float(__builtin_amdgcn_ds_bpermute((lane ^ mask) << 2, __float_as_int(v))); }
; template <bool GROUPNORM>
; DI void wave_tail(f32x4 (&acc)[8][2], int lane, const float* gain, const bf16* gate0, bf16* out0, size_t gate_stride) {
;     ...
; #pragma unroll
;         for (int et = 0; et < 8; ++et)
; #pragma unroll
;             for (int r = 0; r < 4; ++r) { s1 += acc[et][x][r]; s2 += acc[et][x][r] * acc[et][x][r]; }
;         s1 += sx(s1, 16, lane); s1 += sx(s1, 32, lane); s2 += sx(s2, 16, lane); s2 += sx(s2, 32, lane);
;     ...
;             const float y0 = (acc[et][x][0] - mean) * rstd * gn.x * fsilu(bflo(gw.x)), y1 = (acc[et][x][1] - mean) * rstd * gn.y * fsilu(bfhi(gw.x));
;             const float y2 = (acc[et][x][2] - mean) * rstd * gn.z * fsilu(bflo(gw.y)), y3 = (acc[et][x][3] - mean) * rstd * gn.w * fsilu(bfhi(gw.y));
	v_lshlrev_b32_e32 v90, 16, v22
	v_and_b32_e32 v91, 0xffff0000, v22
	v_mul_f32_e32 v22, 0xbfb8aa3b, v90
	v_exp_f32_e32 v22, v22
	s_nop 0
	v_add_f32_e32 v22, 1.0, v22
	v_rcp_f32_e32 v92, v22
	v_mul_f32_e32 v22, 0xbfb8aa3b, v91
	v_exp_f32_e32 v22, v22
	s_nop 0
	v_add_f32_e32 v22, 1.0, v22
	v_rcp_f32_e32 v93, v22
	v_lshlrev_b32_e32 v22, 16, v23
	v_and_b32_e32 v23, 0xffff0000, v23
	v_pk_mul_f32 v[100:101], v[92:93], v[90:91]
	v_mul_f32_e32 v90, 0xbfb8aa3b, v22
	v_mul_f32_e32 v91, 0xbfb8aa3b, v23
	v_exp_f32_e32 v90, v90
	v_exp_f32_e32 v91, v91
	v_add_f32_e32 v90, 1.0, v90
	v_add_f32_e32 v91, 1.0, v91
	v_rcp_f32_e32 v90, v90
	v_rcp_f32_e32 v91, v91
	s_nop 0
	v_pk_mul_f32 v[98:99], v[90:91], v[22:23]
	s_waitcnt vmcnt(11)
	v_lshlrev_b32_e32 v22, 16, v18
	v_and_b32_e32 v23, 0xffff0000, v18
	v_mul_f32_e32 v18, 0xbfb8aa3b, v22
	v_exp_f32_e32 v18, v18
	s_nop 0
	v_add_f32_e32 v18, 1.0, v18
	v_rcp_f32_e32 v90, v18
	v_mul_f32_e32 v18, 0xbfb8aa3b, v23
	v_exp_f32_e32 v18, v18
	s_nop 0
	v_add_f32_e32 v18, 1.0, v18
	v_rcp_f32_e32 v91, v18
	v_lshlrev_b32_e32 v18, 16, v19
	v_and_b32_e32 v19, 0xffff0000, v19
	v_pk_mul_f32 v[92:93], v[90:91], v[22:23]
	v_mul_f32_e32 v22, 0xbfb8aa3b, v18
	v_mul_f32_e32 v23, 0xbfb8aa3b, v19
	v_exp_f32_e32 v22, v22
	v_exp_f32_e32 v23, v23
	v_add_f32_e32 v22, 1.0, v22
	v_add_f32_e32 v23, 1.0, v23
	v_rcp_f32_e32 v22, v22
	v_rcp_f32_e32 v23, v23
	s_nop 0
	v_pk_mul_f32 v[94:95], v[22:23], v[18:19]
	s_waitcnt vmcnt(10)
	v_lshlrev_b32_e32 v18, 16, v14
	v_and_b32_e32 v19, 0xffff0000, v14
	v_mul_f32_e32 v14, 0xbfb8aa3b, v18
	v_exp_f32_e32 v14, v14
	s_nop 0
	v_add_f32_e32 v14, 1.0, v14
	v_rcp_f32_e32 v22, v14
	v_mul_f32_e32 v14, 0xbfb8aa3b, v19
	v_exp_f32_e32 v14, v14
	s_nop 0
	v_add_f32_e32 v14, 1.0, v14
	v_rcp_f32_e32 v23, v14
	v_lshlrev_b32_e32 v14, 16, v15
	v_and_b32_e32 v15, 0xffff0000, v15
	v_pk_mul_f32 v[22:23], v[22:23], v[18:19]
	v_mul_f32_e32 v18, 0xbfb8aa3b, v14
	v_mul_f32_e32 v19, 0xbfb8aa3b, v15
	v_exp_f32_e32 v18, v18
	v_exp_f32_e32 v19, v19
	v_add_f32_e32 v18, 1.0, v18
	v_add_f32_e32 v19, 1.0, v19
	v_rcp_f32_e32 v18, v18
	v_rcp_f32_e32 v19, v19
	s_nop 0
	v_pk_mul_f32 v[90:91], v[18:19], v[14:15]
	s_waitcnt vmcnt(9)
	v_lshlrev_b32_e32 v14, 16, v16
	v_and_b32_e32 v15, 0xffff0000, v16
	v_mul_f32_e32 v16, 0xbfb8aa3b, v14
	v_exp_f32_e32 v16, v16
	s_nop 0
	v_add_f32_e32 v16, 1.0, v16
	v_rcp_f32_e32 v18, v16
	v_mul_f32_e32 v16, 0xbfb8aa3b, v15
	v_exp_f32_e32 v16, v16
	s_nop 0
	v_add_f32_e32 v16, 1.0, v16
	v_rcp_f32_e32 v19, v16
	v_lshlrev_b32_e32 v16, 16, v17
	v_and_b32_e32 v17, 0xffff0000, v17
	v_pk_mul_f32 v[14:15], v[18:19], v[14:15]
	v_mul_f32_e32 v18, 0xbfb8aa3b, v16
	v_mul_f32_e32 v19, 0xbfb8aa3b, v17
	v_exp_f32_e32 v18, v18
	v_exp_f32_e32 v19, v19
	v_add_f32_e32 v18, 1.0, v18
	v_add_f32_e32 v19, 1.0, v19
	v_rcp_f32_e32 v18, v18
	v_rcp_f32_e32 v19, v19
	s_nop 0
	v_pk_mul_f32 v[16:17], v[18:19], v[16:17]
	s_waitcnt vmcnt(8)
	v_lshlrev_b32_e32 v18, 16, v20
	v_and_b32_e32 v19, 0xffff0000, v20
	v_mul_f32_e32 v20, 0xbfb8aa3b, v18
	v_exp_f32_e32 v20, v20
	s_nop 0
	v_add_f32_e32 v20, 1.0, v20
	v_rcp_f32_e32 v138, v20
	v_mul_f32_e32 v20, 0xbfb8aa3b, v19
	v_exp_f32_e32 v20, v20
	s_nop 0
	v_add_f32_e32 v20, 1.0, v20
	v_rcp_f32_e32 v139, v20
	v_lshlrev_b32_e32 v20, 16, v21
	v_mul_f32_e32 v105, 0xbfb8aa3b, v20
	v_exp_f32_e32 v105, v105
	v_and_b32_e32 v21, 0xffff0000, v21
	v_pk_mul_f32 v[18:19], v[138:139], v[18:19]
	v_add_f32_e32 v105, 1.0, v105
	v_rcp_f32_e32 v138, v105
	v_mul_f32_e32 v105, 0xbfb8aa3b, v21
	v_exp_f32_e32 v105, v105
	s_nop 0
	v_add_f32_e32 v105, 1.0, v105
	v_rcp_f32_e32 v139, v105
	s_nop 0
	v_pk_mul_f32 v[20:21], v[138:139], v[20:21]
	v_mov_b32_e32 v138, v72
	v_mov_b32_e32 v139, v88
	v_pk_fma_f32 v[138:139], v[138:139], v[138:139], v[144:145]
	v_mov_b32_e32 v144, v70
	v_mov_b32_e32 v145, v86
	v_pk_fma_f32 v[138:139], v[144:145], v[144:145], v[138:139]
	v_mov_b32_e32 v144, v71
	v_mov_b32_e32 v145, v87
	v_pk_fma_f32 v[138:139], v[144:145], v[144:145], v[138:139]
	v_mov_b32_e32 v144, v68
	v_mov_b32_e32 v145, v84
	v_pk_fma_f32 v[138:139], v[144:145], v[144:145], v[138:139]
	v_mov_b32_e32 v144, v69
	v_mov_b32_e32 v145, v85
	v_pk_fma_f32 v[138:139], v[144:145], v[144:145], v[138:139]
	v_mov_b32_e32 v144, v66
	v_mov_b32_e32 v145, v82
	v_pk_fma_f32 v[138:139], v[144:145], v[144:145], v[138:139]
	v_mov_b32_e32 v144, v67
	v_mov_b32_e32 v145, v83
	v_pk_fma_f32 v[138:139], v[144:145], v[144:145], v[138:139]
	v_mov_b32_e32 v144, v64
	v_mov_b32_e32 v145, v80
	v_pk_fma_f32 v[138:139], v[144:145], v[144:145], v[138:139]
	v_mov_b32_e32 v144, v65
	v_mov_b32_e32 v145, v81
	v_pk_fma_f32 v[138:139], v[144:145], v[144:145], v[138:139]
	v_mov_b32_e32 v144, v62
	v_mov_b32_e32 v145, v78
	v_pk_fma_f32 v[138:139], v[144:145], v[144:145], v[138:139]
	v_mov_b32_e32 v144, v63
	v_mov_b32_e32 v145, v79
	v_pk_fma_f32 v[138:139], v[144:145], v[144:145], v[138:139]
	v_mov_b32_e32 v144, v50
	v_mov_b32_e32 v145, v76
	v_pk_fma_f32 v[138:139], v[144:145], v[144:145], v[138:139]
	v_mov_b32_e32 v144, v51
	v_mov_b32_e32 v145, v77
	v_pk_fma_f32 v[144:145], v[144:145], v[144:145], v[138:139]
	v_pk_mul_f32 v[138:139], v[24:25], v[24:25]
	v_pk_fma_f32 v[144:145], v[146:147], v[146:147], v[144:145]
	v_mov_b32_e32 v146, v49
	v_mov_b32_e32 v147, v75
	v_pk_fma_f32 v[144:145], v[146:147], v[146:147], v[144:145]
	v_mov_b32_e32 v146, v42
	v_mov_b32_e32 v147, v54
	v_pk_fma_f32 v[144:145], v[146:147], v[146:147], v[144:145]
	v_mov_b32_e32 v146, v43
	v_mov_b32_e32 v147, v55
	v_pk_fma_f32 v[144:145], v[146:147], v[146:147], v[144:145]
	v_mov_b32_e32 v146, v40
	v_mov_b32_e32 v147, v52
	v_pk_fma_f32 v[144:145], v[146:147], v[146:147], v[144:145]
	v_mov_b32_e32 v146, v41
	v_mov_b32_e32 v147, v53
	v_pk_fma_f32 v[144:145], v[146:147], v[146:147], v[144:145]
	v_mov_b32_e32 v146, v34
	v_mov_b32_e32 v147, v46
	v_pk_fma_f32 v[144:145], v[146:147], v[146:147], v[144:145]
	v_mov_b32_e32 v146, v35
	v_mov_b32_e32 v147, v47
	v_pk_fma_f32 v[144:145], v[146:147], v[146:147], v[144:145]
	v_mov_b32_e32 v146, v32
	v_mov_b32_e32 v147, v44
	v_pk_fma_f32 v[144:145], v[146:147], v[146:147], v[144:145]
	v_mov_b32_e32 v146, v33
	v_mov_b32_e32 v147, v45
	v_pk_fma_f32 v[144:145], v[146:147], v[146:147], v[144:145]
	v_mov_b32_e32 v146, v148
	v_mov_b32_e32 v147, v136
	v_pk_add_f32 v[144:145], v[146:147], v[144:145]
	v_mov_b32_e32 v136, v149
	v_pk_add_f32 v[136:137], v[136:137], v[144:145]
	v_mov_b32_e32 v144, v138
	v_mov_b32_e32 v145, v130
	v_pk_add_f32 v[136:137], v[144:145], v[136:137]
	v_mov_b32_e32 v130, v139
	v_pk_add_f32 v[130:131], v[130:131], v[136:137]
	v_mov_b32_e32 v136, v150
	v_mov_b32_e32 v137, v128
	v_pk_mul_f32 v[146:147], v[4:5], v[4:5]
	v_pk_add_f32 v[130:131], v[136:137], v[130:131]
	v_mov_b32_e32 v128, v151
	v_pk_add_f32 v[128:129], v[128:129], v[130:131]
	v_mov_b32_e32 v130, v146
	v_mov_b32_e32 v131, v96
	v_pk_add_f32 v[128:129], v[130:131], v[128:129]
	v_mov_b32_e32 v96, v147
	v_pk_add_f32 v[96:97], v[96:97], v[128:129]
	ds_bpermute_b32 v129, v141, v97
	ds_bpermute_b32 v128, v141, v96
	s_waitcnt lgkmcnt(0)
; DI unsigned pk2(float lo, float hi) { f32x2_t v = {lo, hi}; bf16x2_t b = __builtin_convertvector(v, bf16x2_t); return __builtin_bit_cast(unsigned, b); }
; DI float bflo(unsigned w) { return __uint_as_float(w << 16); }
; DI float bfhi(unsigned w) { return __uint_as_float(w & 0xffff0000u); }
; DI float fsilu(float x) { return x * fsigmoid(x); }
; template <bool GROUPNORM>
; DI void wave_tail(f32x4 (&acc)[8][2], int lane, const float* gain, const bf16* gate0, bf16* out0, size_t gate_stride) {
;     ...
;         for (int et = 0; et < 8; ++et) gws[et] = *(const u32x2*)(gate0 + (size_t)(16 * x + lr) * gate_stride + 16 * et + 4 * g);
;     ...
;         const float mean = GROUPNORM ? s1 * (1.f / 128.f) : 0.f;
;         const float var = GROUPNORM ? fmaxf(s2 * (1.f / 128.f) - mean * mean, 0.f) : s2 * (1.f / 128.f);
;         const float rstd = rsqrtf(var + EPS);
;         bf16* op = out0 + (size_t)(16 * x + lr) * 512;
; #pragma unroll
;         for (int et = 0; et < 8; ++et) {
;             const int e0 = 16 * et + 4 * g;
;             const f32x4 gn = *(const f32x4*)(gain + e0);
;             const u32x2 gw = gws[et];
;             const float y0 = (acc[et][x][0] - mean) * rstd * gn.x * fsilu(bflo(gw.x)), y1 = (acc[et][x][1] - mean) * rstd * gn.y * fsilu(bfhi(gw.x));
;             const float y2 = (acc[et][x][2] - mean) * rstd * gn.z * fsilu(bflo(gw.y)), y3 = (acc[et][x][3] - mean) * rstd * gn.w * fsilu(bfhi(gw.y));
;             u32x2 w; w.x = pk2(y0, y1); w.y = pk2(y2, y3);
;             *(u32x2*)(op + e0) = w;
;         }
	v_pk_add_f32 v[96:97], v[96:97], v[128:129]
	ds_bpermute_b32 v129, v142, v97
	ds_bpermute_b32 v128, v142, v96
	s_waitcnt lgkmcnt(0)
	v_pk_add_f32 v[96:97], v[96:97], v[128:129]
	s_nop 0
	v_pk_fma_f32 v[96:97], v[96:97], s[18:19], v[198:199] op_sel_hi:[1,0,0]
	s_nop 0
	v_mul_f32_e32 v105, 0x4b800000, v97
	v_cmp_gt_f32_e64 s[38:39], s67, v97
	v_cmp_gt_f32_e32 vcc, s67, v96
	s_nop 0
	v_cndmask_b32_e64 v97, v97, v105, s[38:39]
	v_rsq_f32_e32 v97, v97
	s_nop 0
	v_mul_f32_e32 v105, 0x45800000, v97
	v_cndmask_b32_e64 v128, v97, v105, s[38:39]
	v_pk_mul_f32 v[88:89], v[88:89], v[128:129] op_sel_hi:[1,0]
	v_pk_mul_f32 v[86:87], v[86:87], v[128:129] op_sel_hi:[1,0]
	s_waitcnt vmcnt(0)
	v_pk_mul_f32 v[0:1], v[200:201], v[88:89]
	v_pk_mul_f32 v[2:3], v[202:203], v[86:87]
	v_pk_mul_f32 v[0:1], v[122:123], v[0:1]
	v_pk_mul_f32 v[2:3], v[102:103], v[2:3]
	v_cvt_pk_bf16_f32 v0, v0, v1
	v_cvt_pk_bf16_f32 v1, v2, v3
	global_store_dwordx2 v[12:13], v[0:1], off
	v_pk_mul_f32 v[84:85], v[84:85], v[128:129] op_sel_hi:[1,0]
	v_pk_mul_f32 v[82:83], v[82:83], v[128:129] op_sel_hi:[1,0]
	v_pk_mul_f32 v[80:81], v[80:81], v[128:129] op_sel_hi:[1,0]
	v_pk_mul_f32 v[78:79], v[78:79], v[128:129] op_sel_hi:[1,0]
	v_pk_mul_f32 v[76:77], v[76:77], v[128:129] op_sel_hi:[1,0]
	v_pk_mul_f32 v[74:75], v[74:75], v[128:129] op_sel_hi:[1,0]
	v_pk_mul_f32 v[54:55], v[54:55], v[128:129] op_sel_hi:[1,0]
	v_pk_mul_f32 v[52:53], v[52:53], v[128:129] op_sel_hi:[1,0]
	v_pk_mul_f32 v[46:47], v[46:47], v[128:129] op_sel_hi:[1,0]
	v_pk_mul_f32 v[0:1], v[204:205], v[84:85]
	v_pk_mul_f32 v[2:3], v[206:207], v[82:83]
	v_pk_mul_f32 v[0:1], v[134:135], v[0:1]
	v_pk_mul_f32 v[2:3], v[132:133], v[2:3]
	v_cvt_pk_bf16_f32 v0, v0, v1
	v_cvt_pk_bf16_f32 v1, v2, v3
	global_store_dwordx2 v[12:13], v[0:1], off offset:32
	v_pk_mul_f32 v[0:1], v[208:209], v[80:81]
	v_pk_mul_f32 v[2:3], v[210:211], v[78:79]
	v_pk_mul_f32 v[0:1], v[126:127], v[0:1]
	v_pk_mul_f32 v[2:3], v[124:125], v[2:3]
	v_cvt_pk_bf16_f32 v0, v0, v1
	v_cvt_pk_bf16_f32 v1, v2, v3
	global_store_dwordx2 v[12:13], v[0:1], off offset:64
	v_pk_mul_f32 v[0:1], v[212:213], v[76:77]
	v_pk_mul_f32 v[2:3], v[214:215], v[74:75]
	v_pk_mul_f32 v[0:1], v[100:101], v[0:1]
	v_pk_mul_f32 v[2:3], v[98:99], v[2:3]
	v_cvt_pk_bf16_f32 v0, v0, v1
	v_cvt_pk_bf16_f32 v1, v2, v3
	global_store_dwordx2 v[12:13], v[0:1], off offset:96
	v_pk_mul_f32 v[0:1], v[216:217], v[54:55]
	v_pk_mul_f32 v[2:3], v[218:219], v[52:53]
	v_pk_mul_f32 v[0:1], v[92:93], v[0:1]
	v_pk_mul_f32 v[2:3], v[94:95], v[2:3]
	v_cvt_pk_bf16_f32 v0, v0, v1
	v_cvt_pk_bf16_f32 v1, v2, v3
	global_store_dwordx2 v[12:13], v[0:1], off offset:128
	v_pk_mul_f32 v[0:1], v[46:47], v[220:221]
	s_nop 0
	v_pk_mul_f32 v[0:1], v[22:23], v[0:1]
	v_pk_mul_f32 v[22:23], v[44:45], v[128:129] op_sel_hi:[1,0]
	v_cvt_pk_bf16_f32 v0, v0, v1
	v_pk_mul_f32 v[2:3], v[22:23], v[222:223]
	v_pk_mul_f32 v[22:23], v[38:39], v[128:129] op_sel_hi:[1,0]
	v_pk_mul_f32 v[2:3], v[90:91], v[2:3]
	s_nop 0
	v_cvt_pk_bf16_f32 v1, v2, v3
	global_store_dwordx2 v[12:13], v[0:1], off offset:160
	v_pk_mul_f32 v[0:1], v[22:23], v[232:233]
	s_nop 0
	v_pk_mul_f32 v[0:1], v[14:15], v[0:1]
	v_pk_mul_f32 v[14:15], v[36:37], v[128:129] op_sel_hi:[1,0]
	v_cvt_pk_bf16_f32 v0, v0, v1
	v_pk_mul_f32 v[2:3], v[14:15], v[234:235]
	v_pk_mul_f32 v[14:15], v[30:31], v[128:129] op_sel_hi:[1,0]
	v_pk_mul_f32 v[2:3], v[16:17], v[2:3]
	s_nop 0
	v_cvt_pk_bf16_f32 v1, v2, v3
	global_store_dwordx2 v[12:13], v[0:1], off offset:192
	v_pk_mul_f32 v[0:1], v[14:15], v[236:237]
	v_pk_mul_f32 v[14:15], v[28:29], v[128:129] op_sel_hi:[1,0]
	v_pk_mul_f32 v[0:1], v[18:19], v[0:1]
	v_pk_mul_f32 v[2:3], v[14:15], v[238:239]
	v_cvt_pk_bf16_f32 v0, v0, v1
	v_pk_mul_f32 v[2:3], v[20:21], v[2:3]
	s_nop 0
	v_cvt_pk_bf16_f32 v1, v2, v3
	global_store_dwordx2 v[12:13], v[0:1], off offset:224
	v_add_co_u32_e64 v0, s[38:39], s2, v8
	s_nop 1
	v_addc_co_u32_e64 v1, s[38:39], 0, v9, s[38:39]
	global_load_dwordx2 v[36:37], v[0:1], off
	global_load_dwordx2 v[22:23], v[0:1], off offset:32
	global_load_dwordx2 v[20:21], v[0:1], off offset:64
	global_load_dwordx2 v[18:19], v[0:1], off offset:96
	global_load_dwordx2 v[16:17], v[0:1], off offset:128
	global_load_dwordx2 v[14:15], v[0:1], off offset:160
	global_load_dwordx2 v[12:13], v[0:1], off offset:192
	global_load_dwordx2 v[2:3], v[0:1], off offset:224
	v_mul_f32_e32 v0, 0x4b800000, v96
	v_cndmask_b32_e32 v0, v96, v0, vcc
	v_rsq_f32_e32 v0, v0
	s_nop 0
	v_mul_f32_e32 v1, 0x45800000, v0
	v_cndmask_b32_e32 v8, v0, v1, vcc
	v_lshl_add_u64 v[0:1], v[10:11], 0, s[14:15]
	s_waitcnt vmcnt(7)
	v_lshlrev_b32_e32 v10, 16, v36
	v_mul_f32_e32 v9, 0xbfb8aa3b, v10
	v_exp_f32_e32 v9, v9
	v_and_b32_e32 v11, 0xffff0000, v36
	v_add_f32_e32 v9, 1.0, v9
	v_rcp_f32_e32 v38, v9
	v_pk_mul_f32 v[44:45], v[72:73], v[8:9] op_sel_hi:[1,0]
	v_mul_f32_e32 v9, 0xbfb8aa3b, v11
	v_exp_f32_e32 v9, v9
	s_waitcnt vmcnt(0)
; DI unsigned pk2(float lo, float hi) { f32x2_t v = {lo, hi}; bf16x2_t b = __builtin_convertvector(v, bf16x2_t); return __builtin_bit_cast(unsigned, b); }
; DI float bflo(unsigned w) { return __uint_as_float(w << 16); }
; DI float bfhi(unsigned w) { return __uint_as_float(w & 0xffff0000u); }
; DI float fsilu(float x) { return x * fsigmoid(x); }
; template <bool GROUPNORM>
; DI void wave_tail(f32x4 (&acc)[8][2], int lane, const float* gain, const bf16* gate0, bf16* out0, size_t gate_stride) {
;     ...
;         for (int et = 0; et < 8; ++et) {
;             const int e0 = 16 * et + 4 * g;
;             const f32x4 gn = *(const f32x4*)(gain + e0);
;             const u32x2 gw = gws[et];
;             const float y0 = (acc[et][x][0] - mean) * rstd * gn.x * fsilu(bflo(gw.x)), y1 = (acc[et][x][1] - mean) * rstd * gn.y * fsilu(bfhi(gw.x));
;             const float y2 = (acc[et][x][2] - mean) * rstd * gn.z * fsilu(bflo(gw.y)), y3 = (acc[et][x][3] - mean) * rstd * gn.w * fsilu(bfhi(gw.y));
;             u32x2 w; w.x = pk2(y0, y1); w.y = pk2(y2, y3);
;             *(u32x2*)(op + e0) = w;
	v_pk_mul_f32 v[28:29], v[200:201], v[44:45]
	v_add_f32_e32 v9, 1.0, v9
	v_rcp_f32_e32 v39, v9
	s_nop 0
	v_pk_mul_f32 v[10:11], v[38:39], v[10:11]
	s_nop 0
	v_pk_mul_f32 v[10:11], v[10:11], v[28:29]
	v_lshlrev_b32_e32 v28, 16, v37
	v_mul_f32_e32 v9, 0xbfb8aa3b, v28
	v_exp_f32_e32 v9, v9
	v_and_b32_e32 v29, 0xffff0000, v37
	v_cvt_pk_bf16_f32 v10, v10, v11
	v_add_f32_e32 v9, 1.0, v9
	v_rcp_f32_e32 v36, v9
	v_pk_mul_f32 v[38:39], v[70:71], v[8:9] op_sel_hi:[1,0]
	v_mul_f32_e32 v9, 0xbfb8aa3b, v29
	v_exp_f32_e32 v9, v9
	v_pk_mul_f32 v[30:31], v[202:203], v[38:39]
	v_add_f32_e32 v9, 1.0, v9
	v_rcp_f32_e32 v37, v9
	s_nop 0
	v_pk_mul_f32 v[28:29], v[36:37], v[28:29]
	s_nop 0
	v_pk_mul_f32 v[28:29], v[28:29], v[30:31]
	s_nop 0
	v_cvt_pk_bf16_f32 v11, v28, v29
	v_lshl_add_u64 v[28:29], v[0:1], 0, v[56:57]
	global_store_dwordx2 v[28:29], v[10:11], off
	v_lshlrev_b32_e32 v10, 16, v22
	v_mul_f32_e32 v9, 0xbfb8aa3b, v10
	v_exp_f32_e32 v9, v9
	v_and_b32_e32 v11, 0xffff0000, v22
	v_lshlrev_b32_e32 v22, 16, v23
	v_and_b32_e32 v23, 0xffff0000, v23
	v_add_f32_e32 v9, 1.0, v9
	v_rcp_f32_e32 v36, v9
	v_pk_mul_f32 v[38:39], v[68:69], v[8:9] op_sel_hi:[1,0]
	v_mul_f32_e32 v9, 0xbfb8aa3b, v11
	v_exp_f32_e32 v9, v9
	v_pk_mul_f32 v[28:29], v[204:205], v[38:39]
	v_add_f32_e32 v9, 1.0, v9
	v_rcp_f32_e32 v37, v9
	v_mul_f32_e32 v9, 0xbfb8aa3b, v22
	v_exp_f32_e32 v9, v9
	v_pk_mul_f32 v[10:11], v[36:37], v[10:11]
	s_nop 0
	v_pk_mul_f32 v[10:11], v[10:11], v[28:29]
	v_add_f32_e32 v9, 1.0, v9
	v_rcp_f32_e32 v28, v9
	v_pk_mul_f32 v[36:37], v[66:67], v[8:9] op_sel_hi:[1,0]
	v_mul_f32_e32 v9, 0xbfb8aa3b, v23
	v_exp_f32_e32 v9, v9
	v_pk_mul_f32 v[30:31], v[206:207], v[36:37]
	v_cvt_pk_bf16_f32 v10, v10, v11
	v_add_f32_e32 v9, 1.0, v9
	v_rcp_f32_e32 v29, v9
	s_nop 0
	v_pk_mul_f32 v[22:23], v[28:29], v[22:23]
	s_nop 0
	v_pk_mul_f32 v[22:23], v[22:23], v[30:31]
	s_nop 0
	v_cvt_pk_bf16_f32 v11, v22, v23
	v_lshl_add_u64 v[22:23], v[0:1], 0, v[108:109]
	global_store_dwordx2 v[22:23], v[10:11], off
	v_lshlrev_b32_e32 v10, 16, v20
	v_mul_f32_e32 v9, 0xbfb8aa3b, v10
	v_exp_f32_e32 v9, v9
	v_and_b32_e32 v11, 0xffff0000, v20
	v_lshlrev_b32_e32 v20, 16, v21
	v_and_b32_e32 v21, 0xffff0000, v21
	v_add_f32_e32 v9, 1.0, v9
	v_rcp_f32_e32 v22, v9
	v_pk_mul_f32 v[36:37], v[64:65], v[8:9] op_sel_hi:[1,0]
	v_mul_f32_e32 v9, 0xbfb8aa3b, v11
	v_exp_f32_e32 v9, v9
	v_pk_mul_f32 v[28:29], v[208:209], v[36:37]
	v_add_f32_e32 v9, 1.0, v9
	v_rcp_f32_e32 v23, v9
	v_mul_f32_e32 v9, 0xbfb8aa3b, v20
	v_exp_f32_e32 v9, v9
	v_pk_mul_f32 v[10:11], v[22:23], v[10:11]
	s_nop 0
	v_pk_mul_f32 v[10:11], v[10:11], v[28:29]
	v_add_f32_e32 v9, 1.0, v9
	v_rcp_f32_e32 v22, v9
	v_pk_mul_f32 v[28:29], v[62:63], v[8:9] op_sel_hi:[1,0]
	v_mul_f32_e32 v9, 0xbfb8aa3b, v21
	v_exp_f32_e32 v9, v9
	v_pk_mul_f32 v[28:29], v[210:211], v[28:29]
	v_cvt_pk_bf16_f32 v10, v10, v11
	v_add_f32_e32 v9, 1.0, v9
	v_rcp_f32_e32 v23, v9
	s_nop 0
	v_pk_mul_f32 v[20:21], v[22:23], v[20:21]
	s_nop 0
	v_pk_mul_f32 v[20:21], v[20:21], v[28:29]
	s_nop 0
	v_cvt_pk_bf16_f32 v11, v20, v21
	v_lshl_add_u64 v[20:21], v[0:1], 0, v[110:111]
	global_store_dwordx2 v[20:21], v[10:11], off
	v_lshlrev_b32_e32 v10, 16, v18
	v_mul_f32_e32 v9, 0xbfb8aa3b, v10
	v_exp_f32_e32 v9, v9
	v_and_b32_e32 v11, 0xffff0000, v18
	v_lshlrev_b32_e32 v18, 16, v19
	v_and_b32_e32 v19, 0xffff0000, v19
	v_add_f32_e32 v9, 1.0, v9
	v_rcp_f32_e32 v28, v9
	v_pk_mul_f32 v[30:31], v[50:51], v[8:9] op_sel_hi:[1,0]
	v_mul_f32_e32 v9, 0xbfb8aa3b, v11
	v_exp_f32_e32 v9, v9
	v_pk_mul_f32 v[20:21], v[212:213], v[30:31]
	v_add_f32_e32 v9, 1.0, v9
	v_rcp_f32_e32 v29, v9
	v_mul_f32_e32 v9, 0xbfb8aa3b, v18
	v_exp_f32_e32 v9, v9
	v_pk_mul_f32 v[10:11], v[28:29], v[10:11]
	s_nop 0
	v_pk_mul_f32 v[10:11], v[10:11], v[20:21]
	v_add_f32_e32 v9, 1.0, v9
	v_rcp_f32_e32 v20, v9
	v_pk_mul_f32 v[28:29], v[48:49], v[8:9] op_sel_hi:[1,0]
	v_mul_f32_e32 v9, 0xbfb8aa3b, v19
	v_exp_f32_e32 v9, v9
	v_pk_mul_f32 v[22:23], v[214:215], v[28:29]
	v_cvt_pk_bf16_f32 v10, v10, v11
	v_add_f32_e32 v9, 1.0, v9
	v_rcp_f32_e32 v21, v9
	s_nop 0
	v_pk_mul_f32 v[18:19], v[20:21], v[18:19]
	s_nop 0
	v_pk_mul_f32 v[18:19], v[18:19], v[22:23]
	s_nop 0
	v_cvt_pk_bf16_f32 v11, v18, v19
	v_lshl_add_u64 v[18:19], v[0:1], 0, v[112:113]
	global_store_dwordx2 v[18:19], v[10:11], off
	v_lshlrev_b32_e32 v10, 16, v16
	v_mul_f32_e32 v9, 0xbfb8aa3b, v10
	v_exp_f32_e32 v9, v9
	v_and_b32_e32 v11, 0xffff0000, v16
; DI unsigned pk2(float lo, float hi) { f32x2_t v = {lo, hi}; bf16x2_t b = __builtin_convertvector(v, bf16x2_t); return __builtin_bit_cast(unsigned, b); }
; DI float bflo(unsigned w) { return __uint_as_float(w << 16); }
; DI float bfhi(unsigned w) { return __uint_as_float(w & 0xffff0000u); }
; DI float fsilu(float x) { return x * fsigmoid(x); }
; template <bool GROUPNORM>
; DI void wave_tail(f32x4 (&acc)[8][2], int lane, const float* gain, const bf16* gate0, bf16* out0, size_t gate_stride) {
;     ...
;         for (int et = 0; et < 8; ++et) {
;             const int e0 = 16 * et + 4 * g;
;             const f32x4 gn = *(const f32x4*)(gain + e0);
;             const u32x2 gw = gws[et];
;             const float y0 = (acc[et][x][0] - mean) * rstd * gn.x * fsilu(bflo(gw.x)), y1 = (acc[et][x][1] - mean) * rstd * gn.y * fsilu(bfhi(gw.x));
;             const float y2 = (acc[et][x][2] - mean) * rstd * gn.z * fsilu(bflo(gw.y)), y3 = (acc[et][x][3] - mean) * rstd * gn.w * fsilu(bfhi(gw.y));
;             u32x2 w; w.x = pk2(y0, y1); w.y = pk2(y2, y3);
;             *(u32x2*)(op + e0) = w;
	v_lshlrev_b32_e32 v16, 16, v17
	v_and_b32_e32 v17, 0xffff0000, v17
	v_add_f32_e32 v9, 1.0, v9
	v_rcp_f32_e32 v22, v9
	v_pk_mul_f32 v[28:29], v[42:43], v[8:9] op_sel_hi:[1,0]
	v_mul_f32_e32 v9, 0xbfb8aa3b, v11
	v_exp_f32_e32 v9, v9
	v_pk_mul_f32 v[18:19], v[216:217], v[28:29]
	v_add_f32_e32 v9, 1.0, v9
	v_rcp_f32_e32 v23, v9
	v_mul_f32_e32 v9, 0xbfb8aa3b, v16
	v_exp_f32_e32 v9, v9
	v_pk_mul_f32 v[10:11], v[22:23], v[10:11]
	s_nop 0
	v_pk_mul_f32 v[10:11], v[10:11], v[18:19]
	v_add_f32_e32 v9, 1.0, v9
	v_rcp_f32_e32 v18, v9
	v_pk_mul_f32 v[22:23], v[40:41], v[8:9] op_sel_hi:[1,0]
	v_mul_f32_e32 v9, 0xbfb8aa3b, v17
	v_exp_f32_e32 v9, v9
	v_pk_mul_f32 v[20:21], v[218:219], v[22:23]
	v_cvt_pk_bf16_f32 v10, v10, v11
	v_add_f32_e32 v9, 1.0, v9
	v_rcp_f32_e32 v19, v9
	s_nop 0
	v_pk_mul_f32 v[16:17], v[18:19], v[16:17]
	s_nop 0
	v_pk_mul_f32 v[16:17], v[16:17], v[20:21]
	s_nop 0
	v_cvt_pk_bf16_f32 v11, v16, v17
	v_lshl_add_u64 v[16:17], v[0:1], 0, v[114:115]
	global_store_dwordx2 v[16:17], v[10:11], off
	v_lshlrev_b32_e32 v10, 16, v14
	v_mul_f32_e32 v9, 0xbfb8aa3b, v10
	v_exp_f32_e32 v9, v9
	v_and_b32_e32 v11, 0xffff0000, v14
	v_lshlrev_b32_e32 v14, 16, v15
	v_and_b32_e32 v15, 0xffff0000, v15
	v_add_f32_e32 v9, 1.0, v9
	v_rcp_f32_e32 v20, v9
	v_pk_mul_f32 v[22:23], v[34:35], v[8:9] op_sel_hi:[1,0]
	v_mul_f32_e32 v9, 0xbfb8aa3b, v11
	v_exp_f32_e32 v9, v9
	v_pk_mul_f32 v[16:17], v[22:23], v[220:221]
	v_add_f32_e32 v9, 1.0, v9
	v_rcp_f32_e32 v21, v9
	v_mul_f32_e32 v9, 0xbfb8aa3b, v14
	v_exp_f32_e32 v9, v9
	v_pk_mul_f32 v[10:11], v[20:21], v[10:11]
	s_nop 0
	v_pk_mul_f32 v[10:11], v[10:11], v[16:17]
	v_add_f32_e32 v9, 1.0, v9
	v_rcp_f32_e32 v16, v9
	v_pk_mul_f32 v[20:21], v[32:33], v[8:9] op_sel_hi:[1,0]
	v_mul_f32_e32 v9, 0xbfb8aa3b, v15
	v_exp_f32_e32 v9, v9
	v_pk_mul_f32 v[18:19], v[20:21], v[222:223]
	v_cvt_pk_bf16_f32 v10, v10, v11
	v_add_f32_e32 v9, 1.0, v9
	v_rcp_f32_e32 v17, v9
	s_nop 0
	v_pk_mul_f32 v[14:15], v[16:17], v[14:15]
	s_nop 0
	v_pk_mul_f32 v[14:15], v[14:15], v[18:19]
	s_nop 0
	v_cvt_pk_bf16_f32 v11, v14, v15
	v_lshl_add_u64 v[14:15], v[0:1], 0, v[116:117]
	global_store_dwordx2 v[14:15], v[10:11], off
	v_lshlrev_b32_e32 v10, 16, v12
	v_mul_f32_e32 v9, 0xbfb8aa3b, v10
	v_exp_f32_e32 v9, v9
	v_and_b32_e32 v11, 0xffff0000, v12
	v_lshlrev_b32_e32 v12, 16, v13
	v_and_b32_e32 v13, 0xffff0000, v13
	v_add_f32_e32 v9, 1.0, v9
	v_rcp_f32_e32 v18, v9
	v_pk_mul_f32 v[20:21], v[26:27], v[8:9] op_sel_hi:[1,0]
	v_mul_f32_e32 v9, 0xbfb8aa3b, v11
	v_exp_f32_e32 v9, v9
	v_pk_mul_f32 v[14:15], v[20:21], v[232:233]
	v_add_f32_e32 v9, 1.0, v9
	v_rcp_f32_e32 v19, v9
	v_mul_f32_e32 v9, 0xbfb8aa3b, v12
	v_exp_f32_e32 v9, v9
	v_pk_mul_f32 v[10:11], v[18:19], v[10:11]
	s_nop 0
	v_pk_mul_f32 v[10:11], v[10:11], v[14:15]
	v_add_f32_e32 v9, 1.0, v9
	v_rcp_f32_e32 v14, v9
	v_pk_mul_f32 v[18:19], v[24:25], v[8:9] op_sel_hi:[1,0]
	v_mul_f32_e32 v9, 0xbfb8aa3b, v13
	v_exp_f32_e32 v9, v9
	v_pk_mul_f32 v[16:17], v[18:19], v[234:235]
	v_cvt_pk_bf16_f32 v10, v10, v11
	v_add_f32_e32 v9, 1.0, v9
	v_rcp_f32_e32 v15, v9
	v_pk_mul_f32 v[6:7], v[6:7], v[8:9] op_sel_hi:[1,0]
	v_pk_mul_f32 v[12:13], v[14:15], v[12:13]
	s_nop 0
	v_pk_mul_f32 v[12:13], v[12:13], v[16:17]
	v_lshlrev_b32_e32 v14, 16, v2
	v_cvt_pk_bf16_f32 v11, v12, v13
	v_lshl_add_u64 v[12:13], v[0:1], 0, v[118:119]
	global_store_dwordx2 v[12:13], v[10:11], off
	v_and_b32_e32 v15, 0xffff0000, v2
	v_mul_f32_e32 v2, 0xbfb8aa3b, v14
	v_exp_f32_e32 v2, v2
	v_lshl_add_u64 v[0:1], v[0:1], 0, v[120:121]
	v_add_f32_e32 v2, 1.0, v2
	v_rcp_f32_e32 v16, v2
	v_mul_f32_e32 v2, 0xbfb8aa3b, v15
	v_exp_f32_e32 v2, v2
	v_pk_mul_f32 v[6:7], v[6:7], v[236:237]
	v_add_f32_e32 v2, 1.0, v2
	v_rcp_f32_e32 v17, v2
	v_lshlrev_b32_e32 v2, 16, v3
	v_mul_f32_e32 v9, 0xbfb8aa3b, v2
	v_exp_f32_e32 v9, v9
	v_and_b32_e32 v3, 0xffff0000, v3
	v_pk_mul_f32 v[10:11], v[16:17], v[14:15]
	v_add_f32_e32 v9, 1.0, v9
	v_pk_mul_f32 v[4:5], v[4:5], v[8:9] op_sel_hi:[1,0]
	v_mul_f32_e32 v8, 0xbfb8aa3b, v3
	v_exp_f32_e32 v8, v8
	v_pk_mul_f32 v[6:7], v[10:11], v[6:7]
	v_rcp_f32_e32 v10, v9
	v_pk_mul_f32 v[4:5], v[4:5], v[238:239]
	v_add_f32_e32 v8, 1.0, v8
	v_rcp_f32_e32 v11, v8
	s_nop 0
	v_pk_mul_f32 v[2:3], v[10:11], v[2:3]
	s_nop 0
	v_pk_mul_f32 v[2:3], v[2:3], v[4:5]
	v_cvt_pk_bf16_f32 v4, v6, v7
	v_cvt_pk_bf16_f32 v5, v2, v3
	global_store_dwordx2 v[0:1], v[4:5], off
	s_cbranch_scc0 .LBB0_507
